# log sites: dropped the hazard pads that only served the deleted compare/select pairs
# baseline (speedup 1.0000x reference)
; __device__ __forceinline__ float silu_f(float x) { return x * __builtin_amdgcn_rcpf(1.f + __expf(-x)); }
;     __device__ __forceinline__ void operator()(const f32x4 (&acc)[2][2][4][2], const pg8::Unit& u, int wr, int wc, int fr, int fq) const {
;     ...
;                 for (int m = 0; m < 4; ++m) rs[ai][m] = rsqrtf(ssq[lrow0 + ai * 128 + m * 16] * (1.f / 1024.f) + EPS);
; #pragma unroll
;             for (int bj = 0; bj < 2; ++bj) {
;                 const int c = c0 + bj * 128;
;                 float lb[8] = {0.f, 0.f, 0.f, 0.f, 0.f, 0.f, 0.f, 0.f};
;                 if (region == 1 && idx != 0) {
;                     const f32x4 a00 = *(const f32x4*)(lbsrc + c), a01 = *(const f32x4*)(lbsrc + c + 4), a10 = *(const f32x4*)(lbsrc + 1024 + c), a11 = *(const f32x4*)(lbsrc + 1024 + c + 4);
; #pragma unroll
;                     for (int j = 0; j < 4; ++j) { lb[j] = __builtin_amdgcn_rcpf(1.f + __expf(a00[j] - a10[j])); lb[4 + j] = __builtin_amdgcn_rcpf(1.f + __expf(a01[j] - a11[j])); }
;                 }
; #pragma unroll
;                 for (int ai = 0; ai < 2; ++ai)
; #pragma unroll
;                     for (int m = 0; m < 4; ++m) {
;                         const int row = lrow0 + ai * 128 + m * 16; const size_t off = (size_t)row * 1024 + c;
;                         const f32x4 v0 = acc[ai][bj][m][0] * rs[ai][m], v1 = acc[ai][bj][m][1] * rs[ai][m];
;                         const float v[8] = {v0[0], v0[1], v0[2], v0[3], v1[0], v1[1], v1[2], v1[3]};
;                         float y[8];
;                         if (region == 0) {
; #pragma unroll
;                             for (int j = 0; j < 8; ++j) y[j] = silu_f(v[j]);
;                             *(v4u*)(o0 + off) = pack8(y);
;                         } else if (region == 1) {
;                             float lf[8];
; #pragma unroll
;                             for (int j = 0; j < 8; ++j) {
;                                 const float om = 1.f - lb[j];
;                                 const float fc = fminf(fmaxf(v[j], -80.f), 80.f);
;                                 const float e = __expf(-fc), sg = __builtin_amdgcn_rcpf(1.f + e);
;                                 y[j] = om * e * sg;
;                                 lf[j] = __logf(fmaxf(lb[j] + om * sg, 1e-30f));
;                             }
;                             *(v4u*)(o1 + off) = pack8(y);
.LBB0_918:
	s_waitcnt vmcnt(0)
	v_fmamk_f32 v150, v154, 0x3a800000, v139
	s_cmp_gt_u32 s39, 3
	s_cselect_b64 s[2:3], -1, 0
	v_rsq_f32_e32 v150, v150
	s_cmp_lg_u32 s13, 2
	v_lshlrev_b64 v[166:167], 10, v[178:179]
	s_cselect_b64 s[46:47], -1, 0
	s_nop 0
	v_mov_b32_e32 v168, v150
	v_pk_mul_f32 v[182:183], v[128:129], v[168:169] op_sel_hi:[1,0]
	v_pk_mul_f32 v[128:129], v[122:123], v[168:169] op_sel_hi:[1,0]
	v_cndmask_b32_e64 v122, 0, 1, s[0:1]
	v_or_b32_e32 v180, v166, v198
	v_mov_b32_e32 v181, v167
	v_pk_mul_f32 v[184:185], v[126:127], v[168:169] op_sel_hi:[1,0]
	v_pk_mul_f32 v[126:127], v[124:125], v[168:169] op_sel_hi:[1,0]
	s_mov_b64 s[20:21], -1
	s_and_b64 vcc, exec, s[2:3]
	v_cmp_ne_u32_e64 s[42:43], 1, v122
	s_cbranch_vccz .LBB0_927
	s_and_b64 vcc, exec, s[42:43]
	s_mov_b64 s[0:1], -1
	s_cbranch_vccnz .LBB0_921
	v_max_f32_e32 v122, v184, v184
	s_mov_b32 s20, 0xc2a00000
	v_med3_f32 v122, v122, s20, v195
	v_mul_f32_e32 v122, 0xbfb8aa3b, v122
	v_exp_f32_e32 v122, v122
	v_pk_add_f32 v[150:151], v[176:177], 1.0 op_sel_hi:[1,0] neg_lo:[1,0] neg_hi:[1,0]
	s_mov_b32 s13, 0x3f317217
	s_mov_b32 s15, 0x7f800000
	v_add_f32_e32 v123, 1.0, v122
	v_rcp_f32_e32 v124, v123
	v_max_f32_e32 v123, v185, v185
	v_med3_f32 v123, v123, s20, v195
	v_mul_f32_e32 v123, 0xbfb8aa3b, v123
	v_exp_f32_e32 v123, v123
	v_pk_add_f32 v[152:153], v[174:175], 1.0 op_sel_hi:[1,0] neg_lo:[1,0] neg_hi:[1,0]
	v_pk_add_f32 v[154:155], v[172:173], 1.0 op_sel_hi:[1,0] neg_lo:[1,0] neg_hi:[1,0]
	v_pk_add_f32 v[158:159], v[170:171], 1.0 op_sel_hi:[1,0] neg_lo:[1,0] neg_hi:[1,0]
	v_add_f32_e32 v125, 1.0, v123
	v_rcp_f32_e32 v125, v125
	v_pk_mul_f32 v[122:123], v[122:123], v[150:151]
	s_nop 0
	v_pk_mul_f32 v[186:187], v[124:125], v[122:123]
	v_fma_f32 v122, v124, v150, v176
	v_max_f32_e32 v122, 0xda24260, v122
	v_log_f32_e32 v122, v122
	s_nop 0
	v_mul_f32_e32 v123, 0x3f317217, v122
	v_fma_f32 v123, v122, s13, -v123
	v_fmac_f32_e32 v123, 0x3377d1cf, v122
	v_fmac_f32_e32 v123, 0x3f317217, v122
	v_mov_b32_e32 v122, v123
	v_fma_f32 v123, v125, v151, v177
	v_max_f32_e32 v123, 0xda24260, v123
	v_log_f32_e32 v123, v123
	s_nop 0
	v_mul_f32_e32 v124, 0x3f317217, v123
	v_fma_f32 v124, v123, s13, -v124
	v_fmac_f32_e32 v124, 0x3377d1cf, v123
	v_fmac_f32_e32 v124, 0x3f317217, v123
	v_mov_b32_e32 v123, v124
	v_max_f32_e32 v124, v182, v182
	v_med3_f32 v124, v124, s20, v195
	v_mul_f32_e32 v124, 0xbfb8aa3b, v124
	v_exp_f32_e32 v124, v124
	s_nop 0
	v_add_f32_e32 v125, 1.0, v124
	v_rcp_f32_e32 v150, v125
	v_max_f32_e32 v125, v183, v183
	v_med3_f32 v125, v125, s20, v195
	v_mul_f32_e32 v125, 0xbfb8aa3b, v125
	v_exp_f32_e32 v125, v125
	s_nop 0
	v_add_f32_e32 v151, 1.0, v125
	v_rcp_f32_e32 v151, v151
	v_pk_mul_f32 v[124:125], v[124:125], v[152:153]
	s_nop 0
	v_pk_mul_f32 v[188:189], v[150:151], v[124:125]
	v_fma_f32 v124, v150, v152, v174
	v_max_f32_e32 v124, 0xda24260, v124
	v_log_f32_e32 v124, v124
	s_nop 0
	v_mul_f32_e32 v125, 0x3f317217, v124
	v_fma_f32 v125, v124, s13, -v125
	v_fmac_f32_e32 v125, 0x3377d1cf, v124
	v_fmac_f32_e32 v125, 0x3f317217, v124
	v_mov_b32_e32 v124, v125
	v_fma_f32 v125, v151, v153, v175
	v_max_f32_e32 v125, 0xda24260, v125
	v_log_f32_e32 v125, v125
	s_nop 0
	v_mul_f32_e32 v150, 0x3f317217, v125
	v_fma_f32 v150, v125, s13, -v150
	v_fmac_f32_e32 v150, 0x3377d1cf, v125
	v_fmac_f32_e32 v150, 0x3f317217, v125
	v_mov_b32_e32 v125, v150
	v_max_f32_e32 v150, v128, v128
	v_med3_f32 v150, v150, s20, v195
	v_mul_f32_e32 v150, 0xbfb8aa3b, v150
	v_exp_f32_e32 v150, v150
	s_nop 0
	v_add_f32_e32 v151, 1.0, v150
	v_rcp_f32_e32 v152, v151
	v_max_f32_e32 v151, v129, v129
	v_med3_f32 v151, v151, s20, v195
	v_mul_f32_e32 v151, 0xbfb8aa3b, v151
	v_exp_f32_e32 v151, v151
	s_nop 0
	v_add_f32_e32 v153, 1.0, v151
	v_rcp_f32_e32 v153, v153
	v_pk_mul_f32 v[150:151], v[150:151], v[154:155]
	s_nop 0
	v_pk_mul_f32 v[156:157], v[152:153], v[150:151]
	v_fma_f32 v150, v152, v154, v172
	v_max_f32_e32 v150, 0xda24260, v150
	v_cvt_pk_bf16_f32 v156, v156, v157
	s_nop 0
	v_log_f32_e32 v150, v150
	s_nop 0
	v_mul_f32_e32 v151, 0x3f317217, v150
	v_fma_f32 v151, v150, s13, -v151
	v_fmac_f32_e32 v151, 0x3377d1cf, v150
	v_fmac_f32_e32 v151, 0x3f317217, v150
	v_mov_b32_e32 v150, v151
	v_fma_f32 v151, v153, v155, v173
	v_max_f32_e32 v151, 0xda24260, v151
	v_log_f32_e32 v151, v151
	s_nop 0
	v_mul_f32_e32 v152, 0x3f317217, v151
	v_fma_f32 v152, v151, s13, -v152
	v_fmac_f32_e32 v152, 0x3377d1cf, v151
	v_fmac_f32_e32 v152, 0x3f317217, v151
	v_mov_b32_e32 v151, v152
	v_max_f32_e32 v152, v126, v126
	v_med3_f32 v152, v152, s20, v195
	v_mul_f32_e32 v152, 0xbfb8aa3b, v152
	v_exp_f32_e32 v152, v152
	s_nop 0
	v_add_f32_e32 v153, 1.0, v152
	v_rcp_f32_e32 v154, v153
	v_max_f32_e32 v153, v127, v127
	v_med3_f32 v153, v153, s20, v195
	v_mul_f32_e32 v153, 0xbfb8aa3b, v153
	v_exp_f32_e32 v153, v153
	s_nop 0
	v_add_f32_e32 v155, 1.0, v153
	v_rcp_f32_e32 v155, v155
	v_pk_mul_f32 v[152:153], v[152:153], v[158:159]
	s_nop 0
	v_pk_mul_f32 v[206:207], v[154:155], v[152:153]
	v_fma_f32 v152, v154, v158, v170
	v_max_f32_e32 v152, 0xda24260, v152
	v_cvt_pk_bf16_f32 v157, v206, v207
	s_nop 0
	v_log_f32_e32 v152, v152
	s_nop 0
	v_mul_f32_e32 v153, 0x3f317217, v152
	v_fma_f32 v153, v152, s13, -v153
	v_fmac_f32_e32 v153, 0x3377d1cf, v152
	v_fmac_f32_e32 v153, 0x3f317217, v152
	v_mov_b32_e32 v152, v153
	v_fma_f32 v153, v155, v159, v171
	v_max_f32_e32 v153, 0xda24260, v153
	v_cvt_pk_bf16_f32 v155, v188, v189
	s_nop 0
	v_log_f32_e32 v153, v153
	s_nop 0
	v_mul_f32_e32 v154, 0x3f317217, v153
	v_fma_f32 v154, v153, s13, -v154
	v_fmac_f32_e32 v154, 0x3377d1cf, v153
	v_fmac_f32_e32 v154, 0x3f317217, v153
	v_mov_b32_e32 v153, v154
	v_readlane_b32 s0, v253, 0
	v_readlane_b32 s1, v253, 1
	v_lshl_add_u64 v[158:159], v[180:181], 1, s[0:1]
	v_readlane_b32 s0, v253, 15
	v_cvt_pk_bf16_f32 v154, v186, v187
	v_readlane_b32 s1, v253, 16
	global_store_dwordx4 v[158:159], v[154:157], off
	s_nop 1
	v_lshl_add_u64 v[154:155], v[180:181], 2, s[0:1]
	s_mov_b64 s[0:1], 0
	global_store_dwordx4 v[154:155], v[122:125], off
	global_store_dwordx4 v[154:155], v[150:153], off offset:16

; __device__ __forceinline__ float silu_f(float x) { return x * __builtin_amdgcn_rcpf(1.f + __expf(-x)); }
;     __device__ __forceinline__ void operator()(const f32x4 (&acc)[2][2][4][2], const pg8::Unit& u, int wr, int wc, int fr, int fq) const {
;     ...
;                 for (int m = 0; m < 4; ++m) rs[ai][m] = rsqrtf(ssq[lrow0 + ai * 128 + m * 16] * (1.f / 1024.f) + EPS);
; #pragma unroll
;             for (int bj = 0; bj < 2; ++bj) {
;                 const int c = c0 + bj * 128;
;                 float lb[8] = {0.f, 0.f, 0.f, 0.f, 0.f, 0.f, 0.f, 0.f};
;                 if (region == 1 && idx != 0) {
;                     const f32x4 a00 = *(const f32x4*)(lbsrc + c), a01 = *(const f32x4*)(lbsrc + c + 4), a10 = *(const f32x4*)(lbsrc + 1024 + c), a11 = *(const f32x4*)(lbsrc + 1024 + c + 4);
; #pragma unroll
;                     for (int j = 0; j < 4; ++j) { lb[j] = __builtin_amdgcn_rcpf(1.f + __expf(a00[j] - a10[j])); lb[4 + j] = __builtin_amdgcn_rcpf(1.f + __expf(a01[j] - a11[j])); }
;                 }
; #pragma unroll
;                 for (int ai = 0; ai < 2; ++ai)
; #pragma unroll
;                     for (int m = 0; m < 4; ++m) {
;                         const int row = lrow0 + ai * 128 + m * 16; const size_t off = (size_t)row * 1024 + c;
;                         const f32x4 v0 = acc[ai][bj][m][0] * rs[ai][m], v1 = acc[ai][bj][m][1] * rs[ai][m];
;                         const float v[8] = {v0[0], v0[1], v0[2], v0[3], v1[0], v1[1], v1[2], v1[3]};
;                         float y[8];
;                         if (region == 0) {
; #pragma unroll
;                             for (int j = 0; j < 8; ++j) y[j] = silu_f(v[j]);
;                             *(v4u*)(o0 + off) = pack8(y);
;                         } else if (region == 1) {
;                             float lf[8];
; #pragma unroll
;                             for (int j = 0; j < 8; ++j) {
;                                 const float om = 1.f - lb[j];
;                                 const float fc = fminf(fmaxf(v[j], -80.f), 80.f);
;                                 const float e = __expf(-fc), sg = __builtin_amdgcn_rcpf(1.f + e);
;                                 y[j] = om * e * sg;
;                                 lf[j] = __logf(fmaxf(lb[j] + om * sg, 1e-30f));
;                             }
;                             *(v4u*)(o1 + off) = pack8(y);
.LBB0_929:
	s_nop 1
	v_fmamk_f32 v122, v205, 0x3a800000, v139
	s_mov_b64 s[0:1], -1
	s_mov_b32 s20, s85
	v_rsq_f32_e32 v124, v122
	v_or_b32_e32 v122, 16, v178
	v_ashrrev_i32_e32 v123, 31, v122
	v_lshlrev_b64 v[122:123], 10, v[122:123]
	s_nop 0
	v_pk_mul_f32 v[128:129], v[120:121], v[124:125] op_sel_hi:[1,0]
	v_pk_mul_f32 v[120:121], v[114:115], v[124:125] op_sel_hi:[1,0]
	v_cndmask_b32_e64 v114, 0, 1, s[2:3]
	s_andn2_b64 vcc, exec, s[2:3]
	v_readlane_b32 s2, v253, 15
	v_or_b32_e32 v126, v122, v198
	v_mov_b32_e32 v127, v123
	v_pk_mul_f32 v[180:181], v[118:119], v[124:125] op_sel_hi:[1,0]
	v_pk_mul_f32 v[118:119], v[116:117], v[124:125] op_sel_hi:[1,0]
	v_cmp_ne_u32_e64 s[44:45], 1, v114
	v_readlane_b32 s3, v253, 16
	s_mov_b32 s21, 0x100000
	s_cbranch_vccnz .LBB0_938
	s_and_b64 vcc, exec, s[42:43]
	s_cbranch_vccnz .LBB0_932
	v_max_f32_e32 v114, v180, v180
	s_mov_b32 s39, 0xc2a00000
	v_med3_f32 v114, v114, s39, v195
	v_mul_f32_e32 v114, 0xbfb8aa3b, v114
	v_exp_f32_e32 v114, v114
	v_pk_add_f32 v[150:151], v[176:177], 1.0 op_sel_hi:[1,0] neg_lo:[1,0] neg_hi:[1,0]
	s_mov_b32 s13, 0x3f317217
	s_mov_b32 s15, 0x7f800000
	v_add_f32_e32 v115, 1.0, v114
	v_rcp_f32_e32 v116, v115
	v_max_f32_e32 v115, v181, v181
	v_med3_f32 v115, v115, s39, v195
	v_mul_f32_e32 v115, 0xbfb8aa3b, v115
	v_exp_f32_e32 v115, v115
	v_pk_add_f32 v[152:153], v[174:175], 1.0 op_sel_hi:[1,0] neg_lo:[1,0] neg_hi:[1,0]
	v_pk_add_f32 v[154:155], v[172:173], 1.0 op_sel_hi:[1,0] neg_lo:[1,0] neg_hi:[1,0]
	v_pk_add_f32 v[158:159], v[170:171], 1.0 op_sel_hi:[1,0] neg_lo:[1,0] neg_hi:[1,0]
	v_add_f32_e32 v117, 1.0, v115
	v_rcp_f32_e32 v117, v117
	v_pk_mul_f32 v[114:115], v[114:115], v[150:151]
	s_nop 0
	v_pk_mul_f32 v[182:183], v[116:117], v[114:115]
	v_fma_f32 v114, v116, v150, v176
	v_max_f32_e32 v114, 0xda24260, v114
	v_log_f32_e32 v114, v114
	s_nop 0
	v_mul_f32_e32 v115, 0x3f317217, v114
	v_fma_f32 v115, v114, s13, -v115
	v_fmac_f32_e32 v115, 0x3377d1cf, v114
	v_fmac_f32_e32 v115, 0x3f317217, v114
	v_mov_b32_e32 v114, v115
	v_fma_f32 v115, v117, v151, v177
	v_max_f32_e32 v115, 0xda24260, v115
	v_log_f32_e32 v115, v115
	s_nop 0
	v_mul_f32_e32 v116, 0x3f317217, v115
	v_fma_f32 v116, v115, s13, -v116
	v_fmac_f32_e32 v116, 0x3377d1cf, v115
	v_fmac_f32_e32 v116, 0x3f317217, v115
	v_mov_b32_e32 v115, v116
	v_max_f32_e32 v116, v128, v128
	v_med3_f32 v116, v116, s39, v195
	v_mul_f32_e32 v116, 0xbfb8aa3b, v116
	v_exp_f32_e32 v116, v116
	s_nop 0
	v_add_f32_e32 v117, 1.0, v116
	v_rcp_f32_e32 v150, v117
	v_max_f32_e32 v117, v129, v129
	v_med3_f32 v117, v117, s39, v195
	v_mul_f32_e32 v117, 0xbfb8aa3b, v117
	v_exp_f32_e32 v117, v117
	s_nop 0
	v_add_f32_e32 v125, 1.0, v117
	v_rcp_f32_e32 v151, v125
	v_pk_mul_f32 v[116:117], v[116:117], v[152:153]
	s_nop 0
	v_pk_mul_f32 v[184:185], v[150:151], v[116:117]
	v_fma_f32 v116, v150, v152, v174
	v_max_f32_e32 v116, 0xda24260, v116
	v_log_f32_e32 v116, v116
	s_nop 0
	v_mul_f32_e32 v117, 0x3f317217, v116
	v_fma_f32 v117, v116, s13, -v117
	v_fmac_f32_e32 v117, 0x3377d1cf, v116
	v_fmac_f32_e32 v117, 0x3f317217, v116
	v_mov_b32_e32 v116, v117
	v_fma_f32 v117, v151, v153, v175
	v_max_f32_e32 v117, 0xda24260, v117
	v_log_f32_e32 v117, v117
	s_nop 0
	v_mul_f32_e32 v125, 0x3f317217, v117
	v_fma_f32 v125, v117, s13, -v125
	v_fmac_f32_e32 v125, 0x3377d1cf, v117
	v_fmac_f32_e32 v125, 0x3f317217, v117
	v_mov_b32_e32 v117, v125
	v_max_f32_e32 v125, v120, v120
	v_med3_f32 v125, v125, s39, v195
	v_mul_f32_e32 v125, 0xbfb8aa3b, v125
	v_exp_f32_e32 v150, v125
	s_nop 0
	v_add_f32_e32 v125, 1.0, v150
	v_rcp_f32_e32 v152, v125
	v_max_f32_e32 v125, v121, v121
	v_med3_f32 v125, v125, s39, v195
	v_mul_f32_e32 v125, 0xbfb8aa3b, v125
	v_exp_f32_e32 v151, v125
	s_nop 0
	v_add_f32_e32 v125, 1.0, v151
	v_rcp_f32_e32 v153, v125
	v_fma_f32 v125, v152, v154, v172
	v_max_f32_e32 v125, 0xda24260, v125
	v_pk_mul_f32 v[150:151], v[150:151], v[154:155]
	v_pk_mul_f32 v[156:157], v[152:153], v[150:151]
	s_nop 0
	v_log_f32_e32 v125, v125
	v_cvt_pk_bf16_f32 v156, v156, v157
	v_mul_f32_e32 v150, 0x3f317217, v125
	v_fma_f32 v150, v125, s13, -v150
	v_fmac_f32_e32 v150, 0x3377d1cf, v125
	v_fmac_f32_e32 v150, 0x3f317217, v125
	v_mov_b32_e32 v125, v150
	v_mov_b32_e32 v150, v125
	v_fma_f32 v125, v153, v155, v173
	v_max_f32_e32 v125, 0xda24260, v125
	v_log_f32_e32 v125, v125
	s_nop 0
	v_mul_f32_e32 v151, 0x3f317217, v125
	v_fma_f32 v151, v125, s13, -v151
	v_fmac_f32_e32 v151, 0x3377d1cf, v125
	v_fmac_f32_e32 v151, 0x3f317217, v125
	v_mov_b32_e32 v125, v151
	v_mov_b32_e32 v151, v125
	v_max_f32_e32 v125, v118, v118
	v_med3_f32 v125, v125, s39, v195
	v_mul_f32_e32 v125, 0xbfb8aa3b, v125
	v_exp_f32_e32 v152, v125
	s_nop 0
	v_add_f32_e32 v125, 1.0, v152
	v_rcp_f32_e32 v154, v125
	v_max_f32_e32 v125, v119, v119
	v_med3_f32 v125, v125, s39, v195
	v_mul_f32_e32 v125, 0xbfb8aa3b, v125
	v_exp_f32_e32 v153, v125
	s_nop 0
	v_add_f32_e32 v125, 1.0, v153
	v_rcp_f32_e32 v155, v125
	v_fma_f32 v125, v154, v158, v170
	v_max_f32_e32 v125, 0xda24260, v125
	v_pk_mul_f32 v[152:153], v[152:153], v[158:159]
	v_pk_mul_f32 v[186:187], v[154:155], v[152:153]
	v_cvt_pk_bf16_f32 v154, v182, v183
	v_log_f32_e32 v125, v125
	v_cvt_pk_bf16_f32 v157, v186, v187
	v_mul_f32_e32 v152, 0x3f317217, v125
	v_fma_f32 v152, v125, s13, -v152
	v_fmac_f32_e32 v152, 0x3377d1cf, v125
	v_fmac_f32_e32 v152, 0x3f317217, v125
	v_mov_b32_e32 v125, v152
	v_mov_b32_e32 v152, v125
	v_fma_f32 v125, v155, v159, v171
	v_max_f32_e32 v125, 0xda24260, v125
	v_cvt_pk_bf16_f32 v155, v184, v185
	s_nop 0
	v_log_f32_e32 v125, v125
	s_nop 0
	v_mul_f32_e32 v153, 0x3f317217, v125
	v_fma_f32 v153, v125, s13, -v153
	v_fmac_f32_e32 v153, 0x3377d1cf, v125
	v_fmac_f32_e32 v153, 0x3f317217, v125
	v_mov_b32_e32 v125, v153
	v_readlane_b32 s0, v253, 0
	v_readlane_b32 s1, v253, 1
	v_mov_b32_e32 v153, v125
	v_lshl_add_u64 v[158:159], v[126:127], 1, s[0:1]
	global_store_dwordx4 v[158:159], v[154:157], off
	s_mov_b64 s[0:1], 0
	s_nop 0
	v_lshl_add_u64 v[154:155], v[126:127], 2, s[2:3]
	global_store_dwordx4 v[154:155], v[114:117], off
	global_store_dwordx4 v[154:155], v[150:153], off offset:16

; __device__ __forceinline__ float silu_f(float x) { return x * __builtin_amdgcn_rcpf(1.f + __expf(-x)); }
;     __device__ __forceinline__ void operator()(const f32x4 (&acc)[2][2][4][2], const pg8::Unit& u, int wr, int wc, int fr, int fq) const {
;     ...
;                 for (int m = 0; m < 4; ++m) rs[ai][m] = rsqrtf(ssq[lrow0 + ai * 128 + m * 16] * (1.f / 1024.f) + EPS);
; #pragma unroll
;             for (int bj = 0; bj < 2; ++bj) {
;                 const int c = c0 + bj * 128;
;                 float lb[8] = {0.f, 0.f, 0.f, 0.f, 0.f, 0.f, 0.f, 0.f};
;                 if (region == 1 && idx != 0) {
;                     const f32x4 a00 = *(const f32x4*)(lbsrc + c), a01 = *(const f32x4*)(lbsrc + c + 4), a10 = *(const f32x4*)(lbsrc + 1024 + c), a11 = *(const f32x4*)(lbsrc + 1024 + c + 4);
; #pragma unroll
;                     for (int j = 0; j < 4; ++j) { lb[j] = __builtin_amdgcn_rcpf(1.f + __expf(a00[j] - a10[j])); lb[4 + j] = __builtin_amdgcn_rcpf(1.f + __expf(a01[j] - a11[j])); }
;                 }
; #pragma unroll
;                 for (int ai = 0; ai < 2; ++ai)
; #pragma unroll
;                     for (int m = 0; m < 4; ++m) {
;                         const int row = lrow0 + ai * 128 + m * 16; const size_t off = (size_t)row * 1024 + c;
;                         const f32x4 v0 = acc[ai][bj][m][0] * rs[ai][m], v1 = acc[ai][bj][m][1] * rs[ai][m];
;                         const float v[8] = {v0[0], v0[1], v0[2], v0[3], v1[0], v1[1], v1[2], v1[3]};
;                         float y[8];
;                         if (region == 0) {
; #pragma unroll
;                             for (int j = 0; j < 8; ++j) y[j] = silu_f(v[j]);
;                             *(v4u*)(o0 + off) = pack8(y);
;                         } else if (region == 1) {
;                             float lf[8];
; #pragma unroll
;                             for (int j = 0; j < 8; ++j) {
;                                 const float om = 1.f - lb[j];
;                                 const float fc = fminf(fmaxf(v[j], -80.f), 80.f);
;                                 const float e = __expf(-fc), sg = __builtin_amdgcn_rcpf(1.f + e);
;                                 y[j] = om * e * sg;
;                                 lf[j] = __logf(fmaxf(lb[j] + om * sg, 1e-30f));
;                             }
;                             *(v4u*)(o1 + off) = pack8(y);
.LBB0_940:
	s_nop 1
	v_fmamk_f32 v114, v204, 0x3a800000, v139
	s_mov_b64 s[0:1], -1
	s_nop 0
	v_rsq_f32_e32 v116, v114
	v_or_b32_e32 v114, 32, v178
	v_ashrrev_i32_e32 v115, 31, v114
	v_lshlrev_b64 v[114:115], 10, v[114:115]
	s_nop 0
	v_or_b32_e32 v118, v114, v198
	v_mov_b32_e32 v119, v115
	v_pk_mul_f32 v[120:121], v[112:113], v[116:117] op_sel_hi:[1,0]
	v_pk_mul_f32 v[126:127], v[110:111], v[116:117] op_sel_hi:[1,0]
	v_pk_mul_f32 v[110:111], v[108:109], v[116:117] op_sel_hi:[1,0]
	v_pk_mul_f32 v[112:113], v[106:107], v[116:117] op_sel_hi:[1,0]
	s_and_b64 vcc, exec, s[44:45]
	s_cbranch_vccnz .LBB0_949
	s_and_b64 vcc, exec, s[42:43]
	s_cbranch_vccnz .LBB0_943
	v_max_f32_e32 v106, v126, v126
	s_mov_b32 s39, 0xc2a00000
	v_med3_f32 v106, v106, s39, v195
	v_mul_f32_e32 v106, 0xbfb8aa3b, v106
	v_exp_f32_e32 v106, v106
	v_pk_add_f32 v[150:151], v[176:177], 1.0 op_sel_hi:[1,0] neg_lo:[1,0] neg_hi:[1,0]
	s_mov_b32 s13, 0x3f317217
	s_mov_b32 s15, 0x7f800000
	v_add_f32_e32 v107, 1.0, v106
	v_rcp_f32_e32 v108, v107
	v_max_f32_e32 v107, v127, v127
	v_med3_f32 v107, v107, s39, v195
	v_mul_f32_e32 v107, 0xbfb8aa3b, v107
	v_exp_f32_e32 v107, v107
	v_pk_add_f32 v[152:153], v[174:175], 1.0 op_sel_hi:[1,0] neg_lo:[1,0] neg_hi:[1,0]
	v_pk_add_f32 v[154:155], v[172:173], 1.0 op_sel_hi:[1,0] neg_lo:[1,0] neg_hi:[1,0]
	v_pk_add_f32 v[158:159], v[170:171], 1.0 op_sel_hi:[1,0] neg_lo:[1,0] neg_hi:[1,0]
	v_add_f32_e32 v109, 1.0, v107
	v_rcp_f32_e32 v109, v109
	v_pk_mul_f32 v[106:107], v[106:107], v[150:151]
	s_nop 0
	v_pk_mul_f32 v[128:129], v[108:109], v[106:107]
	v_fma_f32 v106, v108, v150, v176
	v_max_f32_e32 v106, 0xda24260, v106
	v_log_f32_e32 v106, v106
	s_nop 0
	v_mul_f32_e32 v107, 0x3f317217, v106
	v_fma_f32 v107, v106, s13, -v107
	v_fmac_f32_e32 v107, 0x3377d1cf, v106
	v_fmac_f32_e32 v107, 0x3f317217, v106
	v_mov_b32_e32 v106, v107
	v_fma_f32 v107, v109, v151, v177
	v_max_f32_e32 v107, 0xda24260, v107
	v_log_f32_e32 v107, v107
	s_nop 0
	v_mul_f32_e32 v108, 0x3f317217, v107
	v_fma_f32 v108, v107, s13, -v108
	v_fmac_f32_e32 v108, 0x3377d1cf, v107
	v_fmac_f32_e32 v108, 0x3f317217, v107
	v_mov_b32_e32 v107, v108
	v_max_f32_e32 v108, v120, v120
	v_med3_f32 v108, v108, s39, v195
	v_mul_f32_e32 v108, 0xbfb8aa3b, v108
	v_exp_f32_e32 v108, v108
	s_nop 0
	v_add_f32_e32 v109, 1.0, v108
	v_rcp_f32_e32 v150, v109
	v_max_f32_e32 v109, v121, v121
	v_med3_f32 v109, v109, s39, v195
	v_mul_f32_e32 v109, 0xbfb8aa3b, v109
	v_exp_f32_e32 v109, v109
	s_nop 0
	v_add_f32_e32 v117, 1.0, v109
	v_rcp_f32_e32 v151, v117
	v_pk_mul_f32 v[108:109], v[108:109], v[152:153]
	s_nop 0
	v_pk_mul_f32 v[180:181], v[150:151], v[108:109]
	v_fma_f32 v108, v150, v152, v174
	v_max_f32_e32 v108, 0xda24260, v108
	v_log_f32_e32 v108, v108
	s_nop 0
	v_mul_f32_e32 v109, 0x3f317217, v108
	v_fma_f32 v109, v108, s13, -v109
	v_fmac_f32_e32 v109, 0x3377d1cf, v108
	v_fmac_f32_e32 v109, 0x3f317217, v108
	v_mov_b32_e32 v108, v109
	v_fma_f32 v109, v151, v153, v175
	v_max_f32_e32 v109, 0xda24260, v109
	v_log_f32_e32 v109, v109
	s_nop 0
	v_mul_f32_e32 v117, 0x3f317217, v109
	v_fma_f32 v117, v109, s13, -v117
	v_fmac_f32_e32 v117, 0x3377d1cf, v109
	v_fmac_f32_e32 v117, 0x3f317217, v109
	v_mov_b32_e32 v109, v117
	v_max_f32_e32 v117, v112, v112
	v_med3_f32 v117, v117, s39, v195
	v_mul_f32_e32 v117, 0xbfb8aa3b, v117
	v_exp_f32_e32 v150, v117
	s_nop 0
	v_add_f32_e32 v117, 1.0, v150
	v_rcp_f32_e32 v152, v117
	v_max_f32_e32 v117, v113, v113
	v_med3_f32 v117, v117, s39, v195
	v_mul_f32_e32 v117, 0xbfb8aa3b, v117
	v_exp_f32_e32 v151, v117
	s_nop 0
	v_add_f32_e32 v117, 1.0, v151
	v_rcp_f32_e32 v153, v117
	v_fma_f32 v117, v152, v154, v172
	v_max_f32_e32 v117, 0xda24260, v117
	v_pk_mul_f32 v[150:151], v[150:151], v[154:155]
	s_nop 0
	v_log_f32_e32 v117, v117
	v_pk_mul_f32 v[156:157], v[152:153], v[150:151]
	v_mul_f32_e32 v125, 0x3f317217, v117
	v_fma_f32 v125, v117, s13, -v125
	v_fmac_f32_e32 v125, 0x3377d1cf, v117
	v_fmac_f32_e32 v125, 0x3f317217, v117
	v_cvt_pk_bf16_f32 v156, v156, v157
	s_nop 0
	v_mov_b32_e32 v117, v125
	v_mov_b32_e32 v150, v117
	v_fma_f32 v117, v153, v155, v173
	v_max_f32_e32 v117, 0xda24260, v117
	v_log_f32_e32 v117, v117
	s_nop 0
	v_mul_f32_e32 v125, 0x3f317217, v117
	v_fma_f32 v125, v117, s13, -v125
	v_fmac_f32_e32 v125, 0x3377d1cf, v117
	v_fmac_f32_e32 v125, 0x3f317217, v117
	v_mov_b32_e32 v117, v125
	v_mov_b32_e32 v151, v117
	v_max_f32_e32 v117, v110, v110
	v_med3_f32 v117, v117, s39, v195
	v_mul_f32_e32 v117, 0xbfb8aa3b, v117
	v_exp_f32_e32 v152, v117
	s_nop 0
	v_add_f32_e32 v117, 1.0, v152
	v_rcp_f32_e32 v154, v117
	v_max_f32_e32 v117, v111, v111
	v_med3_f32 v117, v117, s39, v195
	v_mul_f32_e32 v117, 0xbfb8aa3b, v117
	v_exp_f32_e32 v153, v117
	s_nop 0
	v_add_f32_e32 v117, 1.0, v153
	v_rcp_f32_e32 v155, v117
	v_fma_f32 v117, v154, v158, v170
	v_max_f32_e32 v117, 0xda24260, v117
	v_pk_mul_f32 v[152:153], v[152:153], v[158:159]
	s_nop 0
	v_log_f32_e32 v117, v117
	v_pk_mul_f32 v[182:183], v[154:155], v[152:153]
	v_cvt_pk_bf16_f32 v154, v128, v129
	v_cvt_pk_bf16_f32 v157, v182, v183
	v_mul_f32_e32 v125, 0x3f317217, v117
	v_fma_f32 v125, v117, s13, -v125
	v_fmac_f32_e32 v125, 0x3377d1cf, v117
	v_fmac_f32_e32 v125, 0x3f317217, v117
	v_mov_b32_e32 v117, v125
	v_mov_b32_e32 v152, v117
	v_fma_f32 v117, v155, v159, v171
	v_max_f32_e32 v117, 0xda24260, v117
	v_cvt_pk_bf16_f32 v155, v180, v181
	s_nop 0
	v_log_f32_e32 v117, v117
	s_nop 0
	v_mul_f32_e32 v125, 0x3f317217, v117
	v_fma_f32 v125, v117, s13, -v125
	v_fmac_f32_e32 v125, 0x3377d1cf, v117
	v_fmac_f32_e32 v125, 0x3f317217, v117
	v_mov_b32_e32 v117, v125
	v_readlane_b32 s0, v253, 0
	v_readlane_b32 s1, v253, 1
	v_mov_b32_e32 v153, v117
	v_lshl_add_u64 v[128:129], v[118:119], 1, s[0:1]
	global_store_dwordx4 v[128:129], v[154:157], off
	v_lshl_add_u64 v[128:129], v[118:119], 2, s[2:3]
	s_mov_b64 s[0:1], 0
	global_store_dwordx4 v[128:129], v[106:109], off
	global_store_dwordx4 v[128:129], v[150:153], off offset:16

; __device__ __forceinline__ float silu_f(float x) { return x * __builtin_amdgcn_rcpf(1.f + __expf(-x)); }
;     __device__ __forceinline__ void operator()(const f32x4 (&acc)[2][2][4][2], const pg8::Unit& u, int wr, int wc, int fr, int fq) const {
;     ...
;                 for (int m = 0; m < 4; ++m) rs[ai][m] = rsqrtf(ssq[lrow0 + ai * 128 + m * 16] * (1.f / 1024.f) + EPS);
; #pragma unroll
;             for (int bj = 0; bj < 2; ++bj) {
;                 const int c = c0 + bj * 128;
;                 float lb[8] = {0.f, 0.f, 0.f, 0.f, 0.f, 0.f, 0.f, 0.f};
;                 if (region == 1 && idx != 0) {
;                     const f32x4 a00 = *(const f32x4*)(lbsrc + c), a01 = *(const f32x4*)(lbsrc + c + 4), a10 = *(const f32x4*)(lbsrc + 1024 + c), a11 = *(const f32x4*)(lbsrc + 1024 + c + 4);
; #pragma unroll
;                     for (int j = 0; j < 4; ++j) { lb[j] = __builtin_amdgcn_rcpf(1.f + __expf(a00[j] - a10[j])); lb[4 + j] = __builtin_amdgcn_rcpf(1.f + __expf(a01[j] - a11[j])); }
;                 }
; #pragma unroll
;                 for (int ai = 0; ai < 2; ++ai)
; #pragma unroll
;                     for (int m = 0; m < 4; ++m) {
;                         const int row = lrow0 + ai * 128 + m * 16; const size_t off = (size_t)row * 1024 + c;
;                         const f32x4 v0 = acc[ai][bj][m][0] * rs[ai][m], v1 = acc[ai][bj][m][1] * rs[ai][m];
;                         const float v[8] = {v0[0], v0[1], v0[2], v0[3], v1[0], v1[1], v1[2], v1[3]};
;                         float y[8];
;                         if (region == 0) {
; #pragma unroll
;                             for (int j = 0; j < 8; ++j) y[j] = silu_f(v[j]);
;                             *(v4u*)(o0 + off) = pack8(y);
;                         } else if (region == 1) {
;                             float lf[8];
; #pragma unroll
;                             for (int j = 0; j < 8; ++j) {
;                                 const float om = 1.f - lb[j];
;                                 const float fc = fminf(fmaxf(v[j], -80.f), 80.f);
;                                 const float e = __expf(-fc), sg = __builtin_amdgcn_rcpf(1.f + e);
;                                 y[j] = om * e * sg;
;                                 lf[j] = __logf(fmaxf(lb[j] + om * sg, 1e-30f));
;                             }
;                             *(v4u*)(o1 + off) = pack8(y);
.LBB0_951:
	s_nop 1
	v_fmamk_f32 v106, v203, 0x3a800000, v139
	s_mov_b64 s[0:1], -1
	s_nop 0
	v_rsq_f32_e32 v108, v106
	v_or_b32_e32 v106, 48, v178
	v_ashrrev_i32_e32 v107, 31, v106
	v_lshlrev_b64 v[106:107], 10, v[106:107]
	s_nop 0
	v_or_b32_e32 v110, v106, v198
	v_mov_b32_e32 v111, v107
	v_pk_mul_f32 v[112:113], v[104:105], v[108:109] op_sel_hi:[1,0]
	v_pk_mul_f32 v[118:119], v[102:103], v[108:109] op_sel_hi:[1,0]
	v_pk_mul_f32 v[102:103], v[100:101], v[108:109] op_sel_hi:[1,0]
	v_pk_mul_f32 v[104:105], v[98:99], v[108:109] op_sel_hi:[1,0]
	s_and_b64 vcc, exec, s[44:45]
	s_cbranch_vccnz .LBB0_960
	s_and_b64 vcc, exec, s[42:43]
	s_cbranch_vccnz .LBB0_954
	v_max_f32_e32 v98, v118, v118
	s_mov_b32 s39, 0xc2a00000
	v_med3_f32 v98, v98, s39, v195
	v_mul_f32_e32 v98, 0xbfb8aa3b, v98
	v_exp_f32_e32 v98, v98
	v_pk_add_f32 v[126:127], v[176:177], 1.0 op_sel_hi:[1,0] neg_lo:[1,0] neg_hi:[1,0]
	s_mov_b32 s13, 0x3f317217
	s_mov_b32 s15, 0x7f800000
	v_add_f32_e32 v99, 1.0, v98
	v_rcp_f32_e32 v100, v99
	v_max_f32_e32 v99, v119, v119
	v_med3_f32 v99, v99, s39, v195
	v_mul_f32_e32 v99, 0xbfb8aa3b, v99
	v_exp_f32_e32 v99, v99
	v_pk_add_f32 v[150:151], v[174:175], 1.0 op_sel_hi:[1,0] neg_lo:[1,0] neg_hi:[1,0]
	v_pk_add_f32 v[152:153], v[172:173], 1.0 op_sel_hi:[1,0] neg_lo:[1,0] neg_hi:[1,0]
	v_pk_add_f32 v[156:157], v[170:171], 1.0 op_sel_hi:[1,0] neg_lo:[1,0] neg_hi:[1,0]
	v_add_f32_e32 v101, 1.0, v99
	v_rcp_f32_e32 v101, v101
	v_pk_mul_f32 v[98:99], v[98:99], v[126:127]
	s_nop 0
	v_pk_mul_f32 v[120:121], v[100:101], v[98:99]
	v_fma_f32 v98, v100, v126, v176
	v_max_f32_e32 v98, 0xda24260, v98
	v_log_f32_e32 v98, v98
	s_nop 0
	v_mul_f32_e32 v99, 0x3f317217, v98
	v_fma_f32 v99, v98, s13, -v99
	v_fmac_f32_e32 v99, 0x3377d1cf, v98
	v_fmac_f32_e32 v99, 0x3f317217, v98
	v_mov_b32_e32 v98, v99
	v_fma_f32 v99, v101, v127, v177
	v_max_f32_e32 v99, 0xda24260, v99
	v_log_f32_e32 v99, v99
	s_nop 0
	v_mul_f32_e32 v100, 0x3f317217, v99
	v_fma_f32 v100, v99, s13, -v100
	v_fmac_f32_e32 v100, 0x3377d1cf, v99
	v_fmac_f32_e32 v100, 0x3f317217, v99
	v_mov_b32_e32 v99, v100
	v_max_f32_e32 v100, v112, v112
	v_med3_f32 v100, v100, s39, v195
	v_mul_f32_e32 v100, 0xbfb8aa3b, v100
	v_exp_f32_e32 v100, v100
	s_nop 0
	v_add_f32_e32 v101, 1.0, v100
	v_rcp_f32_e32 v128, v101
	v_max_f32_e32 v101, v113, v113
	v_med3_f32 v101, v101, s39, v195
	v_mul_f32_e32 v101, 0xbfb8aa3b, v101
	v_exp_f32_e32 v101, v101
	s_nop 0
	v_add_f32_e32 v109, 1.0, v101
	v_rcp_f32_e32 v129, v109
	v_pk_mul_f32 v[100:101], v[100:101], v[150:151]
	s_nop 0
	v_pk_mul_f32 v[126:127], v[128:129], v[100:101]
	v_fma_f32 v100, v128, v150, v174
	v_max_f32_e32 v100, 0xda24260, v100
	v_log_f32_e32 v100, v100
	s_nop 0
	v_mul_f32_e32 v101, 0x3f317217, v100
	v_fma_f32 v101, v100, s13, -v101
	v_fmac_f32_e32 v101, 0x3377d1cf, v100
	v_fmac_f32_e32 v101, 0x3f317217, v100
	v_mov_b32_e32 v100, v101
	v_fma_f32 v101, v129, v151, v175
	v_max_f32_e32 v101, 0xda24260, v101
	v_log_f32_e32 v101, v101
	s_nop 0
	v_mul_f32_e32 v109, 0x3f317217, v101
	v_fma_f32 v109, v101, s13, -v109
	v_fmac_f32_e32 v109, 0x3377d1cf, v101
	v_fmac_f32_e32 v109, 0x3f317217, v101
	v_mov_b32_e32 v101, v109
	v_max_f32_e32 v109, v104, v104
	v_med3_f32 v109, v109, s39, v195
	v_mul_f32_e32 v109, 0xbfb8aa3b, v109
	v_exp_f32_e32 v128, v109
	s_nop 0
	v_add_f32_e32 v109, 1.0, v128
	v_rcp_f32_e32 v150, v109
	v_max_f32_e32 v109, v105, v105
	v_med3_f32 v109, v109, s39, v195
	v_mul_f32_e32 v109, 0xbfb8aa3b, v109
	v_exp_f32_e32 v129, v109
	s_nop 0
	v_add_f32_e32 v109, 1.0, v129
	v_rcp_f32_e32 v151, v109
	v_fma_f32 v109, v150, v152, v172
	v_max_f32_e32 v109, 0xda24260, v109
	v_pk_mul_f32 v[128:129], v[128:129], v[152:153]
	s_nop 0
	v_log_f32_e32 v109, v109
	v_pk_mul_f32 v[128:129], v[150:151], v[128:129]
	v_mul_f32_e32 v117, 0x3f317217, v109
	v_fma_f32 v117, v109, s13, -v117
	v_fmac_f32_e32 v117, 0x3377d1cf, v109
	v_fmac_f32_e32 v117, 0x3f317217, v109
	v_mov_b32_e32 v109, v117
	v_mov_b32_e32 v150, v109
	v_fma_f32 v109, v151, v153, v173
	v_max_f32_e32 v109, 0xda24260, v109
	v_log_f32_e32 v109, v109
	s_nop 0
	v_mul_f32_e32 v117, 0x3f317217, v109
	v_fma_f32 v117, v109, s13, -v117
	v_fmac_f32_e32 v117, 0x3377d1cf, v109
	v_fmac_f32_e32 v117, 0x3f317217, v109
	v_mov_b32_e32 v109, v117
	v_mov_b32_e32 v151, v109
	v_max_f32_e32 v109, v102, v102
	v_med3_f32 v109, v109, s39, v195
	v_mul_f32_e32 v109, 0xbfb8aa3b, v109
	v_exp_f32_e32 v152, v109
	s_nop 0
	v_add_f32_e32 v109, 1.0, v152
	v_rcp_f32_e32 v154, v109
	v_max_f32_e32 v109, v103, v103
	v_med3_f32 v109, v109, s39, v195
	v_mul_f32_e32 v109, 0xbfb8aa3b, v109
	v_exp_f32_e32 v153, v109
	s_nop 0
	v_add_f32_e32 v109, 1.0, v153
	v_rcp_f32_e32 v155, v109
	v_fma_f32 v109, v154, v156, v170
	v_max_f32_e32 v109, 0xda24260, v109
	v_pk_mul_f32 v[152:153], v[152:153], v[156:157]
	v_cvt_pk_bf16_f32 v156, v128, v129
	v_log_f32_e32 v109, v109
	v_pk_mul_f32 v[158:159], v[154:155], v[152:153]
	v_cvt_pk_bf16_f32 v154, v120, v121
	v_mul_f32_e32 v117, 0x3f317217, v109
	v_fma_f32 v117, v109, s13, -v117
	v_fmac_f32_e32 v117, 0x3377d1cf, v109
	v_fmac_f32_e32 v117, 0x3f317217, v109
	v_mov_b32_e32 v109, v117
	v_mov_b32_e32 v152, v109
	v_fma_f32 v109, v155, v157, v171
	v_max_f32_e32 v109, 0xda24260, v109
	v_cvt_pk_bf16_f32 v155, v126, v127
	v_cvt_pk_bf16_f32 v157, v158, v159
	v_log_f32_e32 v109, v109
	s_nop 0
	v_mul_f32_e32 v117, 0x3f317217, v109
	v_fma_f32 v117, v109, s13, -v117
	v_fmac_f32_e32 v117, 0x3377d1cf, v109
	v_fmac_f32_e32 v117, 0x3f317217, v109
	v_mov_b32_e32 v109, v117
	v_readlane_b32 s0, v253, 0
	v_readlane_b32 s1, v253, 1
	v_mov_b32_e32 v153, v109
	v_lshl_add_u64 v[120:121], v[110:111], 1, s[0:1]
	global_store_dwordx4 v[120:121], v[154:157], off
	v_lshl_add_u64 v[120:121], v[110:111], 2, s[2:3]
	s_mov_b64 s[0:1], 0
	global_store_dwordx4 v[120:121], v[98:101], off
	global_store_dwordx4 v[120:121], v[150:153], off offset:16

; __device__ __forceinline__ float silu_f(float x) { return x * __builtin_amdgcn_rcpf(1.f + __expf(-x)); }
;     __device__ __forceinline__ void operator()(const f32x4 (&acc)[2][2][4][2], const pg8::Unit& u, int wr, int wc, int fr, int fq) const {
;     ...
;                 for (int m = 0; m < 4; ++m) rs[ai][m] = rsqrtf(ssq[lrow0 + ai * 128 + m * 16] * (1.f / 1024.f) + EPS);
; #pragma unroll
;             for (int bj = 0; bj < 2; ++bj) {
;                 const int c = c0 + bj * 128;
;                 float lb[8] = {0.f, 0.f, 0.f, 0.f, 0.f, 0.f, 0.f, 0.f};
;                 if (region == 1 && idx != 0) {
;                     const f32x4 a00 = *(const f32x4*)(lbsrc + c), a01 = *(const f32x4*)(lbsrc + c + 4), a10 = *(const f32x4*)(lbsrc + 1024 + c), a11 = *(const f32x4*)(lbsrc + 1024 + c + 4);
; #pragma unroll
;                     for (int j = 0; j < 4; ++j) { lb[j] = __builtin_amdgcn_rcpf(1.f + __expf(a00[j] - a10[j])); lb[4 + j] = __builtin_amdgcn_rcpf(1.f + __expf(a01[j] - a11[j])); }
;                 }
; #pragma unroll
;                 for (int ai = 0; ai < 2; ++ai)
; #pragma unroll
;                     for (int m = 0; m < 4; ++m) {
;                         const int row = lrow0 + ai * 128 + m * 16; const size_t off = (size_t)row * 1024 + c;
;                         const f32x4 v0 = acc[ai][bj][m][0] * rs[ai][m], v1 = acc[ai][bj][m][1] * rs[ai][m];
;                         const float v[8] = {v0[0], v0[1], v0[2], v0[3], v1[0], v1[1], v1[2], v1[3]};
;                         float y[8];
;                         if (region == 0) {
; #pragma unroll
;                             for (int j = 0; j < 8; ++j) y[j] = silu_f(v[j]);
;                             *(v4u*)(o0 + off) = pack8(y);
;                         } else if (region == 1) {
;                             float lf[8];
; #pragma unroll
;                             for (int j = 0; j < 8; ++j) {
;                                 const float om = 1.f - lb[j];
;                                 const float fc = fminf(fmaxf(v[j], -80.f), 80.f);
;                                 const float e = __expf(-fc), sg = __builtin_amdgcn_rcpf(1.f + e);
;                                 y[j] = om * e * sg;
;                                 lf[j] = __logf(fmaxf(lb[j] + om * sg, 1e-30f));
;                             }
;                             *(v4u*)(o1 + off) = pack8(y);
.LBB0_962:
	s_nop 1
	v_fmamk_f32 v98, v202, 0x3a800000, v139
	s_mov_b64 s[0:1], 0x20000
	s_nop 0
	v_rsq_f32_e32 v100, v98
	v_lshlrev_b64 v[98:99], 10, v[178:179]
	v_lshl_add_u64 v[98:99], v[98:99], 0, s[0:1]
	v_or_b32_e32 v102, v98, v198
	s_nop 0
	v_mov_b32_e32 v103, v99
	v_pk_mul_f32 v[104:105], v[96:97], v[100:101] op_sel_hi:[1,0]
	v_pk_mul_f32 v[110:111], v[94:95], v[100:101] op_sel_hi:[1,0]
	v_pk_mul_f32 v[94:95], v[92:93], v[100:101] op_sel_hi:[1,0]
	v_pk_mul_f32 v[96:97], v[90:91], v[100:101] op_sel_hi:[1,0]
	s_and_b64 vcc, exec, s[44:45]
	s_mov_b64 s[0:1], -1
	s_cbranch_vccnz .LBB0_971
	s_and_b64 vcc, exec, s[42:43]
	s_cbranch_vccnz .LBB0_965
	v_max_f32_e32 v90, v110, v110
	s_mov_b32 s39, 0xc2a00000
	v_med3_f32 v90, v90, s39, v195
	v_mul_f32_e32 v90, 0xbfb8aa3b, v90
	v_exp_f32_e32 v90, v90
	v_pk_add_f32 v[118:119], v[176:177], 1.0 op_sel_hi:[1,0] neg_lo:[1,0] neg_hi:[1,0]
	s_mov_b32 s13, 0x3f317217
	s_mov_b32 s15, 0x7f800000
	v_add_f32_e32 v91, 1.0, v90
	v_rcp_f32_e32 v92, v91
	v_max_f32_e32 v91, v111, v111
	v_med3_f32 v91, v91, s39, v195
	v_mul_f32_e32 v91, 0xbfb8aa3b, v91
	v_exp_f32_e32 v91, v91
	v_pk_add_f32 v[126:127], v[174:175], 1.0 op_sel_hi:[1,0] neg_lo:[1,0] neg_hi:[1,0]
	v_pk_add_f32 v[128:129], v[172:173], 1.0 op_sel_hi:[1,0] neg_lo:[1,0] neg_hi:[1,0]
	v_pk_add_f32 v[152:153], v[170:171], 1.0 op_sel_hi:[1,0] neg_lo:[1,0] neg_hi:[1,0]
	v_add_f32_e32 v93, 1.0, v91
	v_rcp_f32_e32 v93, v93
	v_pk_mul_f32 v[90:91], v[90:91], v[118:119]
	s_nop 0
	v_pk_mul_f32 v[112:113], v[92:93], v[90:91]
	v_fma_f32 v90, v92, v118, v176
	v_max_f32_e32 v90, 0xda24260, v90
	v_log_f32_e32 v90, v90
	s_nop 0
	v_mul_f32_e32 v91, 0x3f317217, v90
	v_fma_f32 v91, v90, s13, -v91
	v_fmac_f32_e32 v91, 0x3377d1cf, v90
	v_fmac_f32_e32 v91, 0x3f317217, v90
	v_mov_b32_e32 v90, v91
	v_fma_f32 v91, v93, v119, v177
	v_max_f32_e32 v91, 0xda24260, v91
	v_log_f32_e32 v91, v91
	s_nop 0
	v_mul_f32_e32 v92, 0x3f317217, v91
	v_fma_f32 v92, v91, s13, -v92
	v_fmac_f32_e32 v92, 0x3377d1cf, v91
	v_fmac_f32_e32 v92, 0x3f317217, v91
	v_mov_b32_e32 v91, v92
	v_max_f32_e32 v92, v104, v104
	v_med3_f32 v92, v92, s39, v195
	v_mul_f32_e32 v92, 0xbfb8aa3b, v92
	v_exp_f32_e32 v92, v92
	s_nop 0
	v_add_f32_e32 v93, 1.0, v92
	v_rcp_f32_e32 v120, v93
	v_max_f32_e32 v93, v105, v105
	v_med3_f32 v93, v93, s39, v195
	v_mul_f32_e32 v93, 0xbfb8aa3b, v93
	v_exp_f32_e32 v93, v93
	s_nop 0
	v_add_f32_e32 v101, 1.0, v93
	v_rcp_f32_e32 v121, v101
	v_pk_mul_f32 v[92:93], v[92:93], v[126:127]
	s_nop 0
	v_pk_mul_f32 v[118:119], v[120:121], v[92:93]
	v_fma_f32 v92, v120, v126, v174
	v_max_f32_e32 v92, 0xda24260, v92
	v_log_f32_e32 v92, v92
	s_nop 0
	v_mul_f32_e32 v93, 0x3f317217, v92
	v_fma_f32 v93, v92, s13, -v93
	v_fmac_f32_e32 v93, 0x3377d1cf, v92
	v_fmac_f32_e32 v93, 0x3f317217, v92
	v_mov_b32_e32 v92, v93
	v_fma_f32 v93, v121, v127, v175
	v_max_f32_e32 v93, 0xda24260, v93
	v_log_f32_e32 v93, v93
	s_nop 0
	v_mul_f32_e32 v101, 0x3f317217, v93
	v_fma_f32 v101, v93, s13, -v101
	v_fmac_f32_e32 v101, 0x3377d1cf, v93
	v_fmac_f32_e32 v101, 0x3f317217, v93
	v_mov_b32_e32 v93, v101
	v_max_f32_e32 v101, v96, v96
	v_med3_f32 v101, v101, s39, v195
	v_mul_f32_e32 v101, 0xbfb8aa3b, v101
	v_exp_f32_e32 v120, v101
	s_nop 0
	v_add_f32_e32 v101, 1.0, v120
	v_rcp_f32_e32 v126, v101
	v_max_f32_e32 v101, v97, v97
	v_med3_f32 v101, v101, s39, v195
	v_mul_f32_e32 v101, 0xbfb8aa3b, v101
	v_exp_f32_e32 v121, v101
	s_nop 0
	v_add_f32_e32 v101, 1.0, v121
	v_rcp_f32_e32 v127, v101
	v_fma_f32 v101, v126, v128, v172
	v_max_f32_e32 v101, 0xda24260, v101
	v_pk_mul_f32 v[120:121], v[120:121], v[128:129]
	s_nop 0
	v_log_f32_e32 v101, v101
	v_pk_mul_f32 v[120:121], v[126:127], v[120:121]
	v_mul_f32_e32 v109, 0x3f317217, v101
	v_fma_f32 v109, v101, s13, -v109
	v_fmac_f32_e32 v109, 0x3377d1cf, v101
	v_fmac_f32_e32 v109, 0x3f317217, v101
	v_mov_b32_e32 v101, v109
	v_mov_b32_e32 v126, v101
	v_fma_f32 v101, v127, v129, v173
	v_max_f32_e32 v101, 0xda24260, v101
	v_log_f32_e32 v101, v101
	s_nop 0
	v_mul_f32_e32 v109, 0x3f317217, v101
	v_fma_f32 v109, v101, s13, -v109
	v_fmac_f32_e32 v109, 0x3377d1cf, v101
	v_fmac_f32_e32 v109, 0x3f317217, v101
	v_mov_b32_e32 v101, v109
	v_mov_b32_e32 v127, v101
	v_max_f32_e32 v101, v94, v94
	v_med3_f32 v101, v101, s39, v195
	v_mul_f32_e32 v101, 0xbfb8aa3b, v101
	v_exp_f32_e32 v128, v101
	s_nop 0
	v_add_f32_e32 v101, 1.0, v128
	v_rcp_f32_e32 v150, v101
	v_max_f32_e32 v101, v95, v95
	v_med3_f32 v101, v101, s39, v195
	v_mul_f32_e32 v101, 0xbfb8aa3b, v101
	v_exp_f32_e32 v129, v101
	s_nop 0
	v_add_f32_e32 v101, 1.0, v129
	v_rcp_f32_e32 v151, v101
	v_fma_f32 v101, v150, v152, v170
	v_max_f32_e32 v101, 0xda24260, v101
	v_pk_mul_f32 v[128:129], v[128:129], v[152:153]
	v_cvt_pk_bf16_f32 v152, v120, v121
	v_log_f32_e32 v101, v101
	v_pk_mul_f32 v[154:155], v[150:151], v[128:129]
	v_cvt_pk_bf16_f32 v150, v112, v113
	v_mul_f32_e32 v109, 0x3f317217, v101
	v_fma_f32 v109, v101, s13, -v109
	v_fmac_f32_e32 v109, 0x3377d1cf, v101
	v_fmac_f32_e32 v109, 0x3f317217, v101
	v_mov_b32_e32 v101, v109
	v_mov_b32_e32 v128, v101
	v_fma_f32 v101, v151, v153, v171
	v_max_f32_e32 v101, 0xda24260, v101
	v_cvt_pk_bf16_f32 v151, v118, v119
	v_cvt_pk_bf16_f32 v153, v154, v155
	v_log_f32_e32 v101, v101
	s_nop 0
	v_mul_f32_e32 v109, 0x3f317217, v101
	v_fma_f32 v109, v101, s13, -v109
	v_fmac_f32_e32 v109, 0x3377d1cf, v101
	v_fmac_f32_e32 v109, 0x3f317217, v101
	v_mov_b32_e32 v101, v109
	v_readlane_b32 s0, v253, 0
	v_readlane_b32 s1, v253, 1
	v_mov_b32_e32 v129, v101
	v_lshl_add_u64 v[112:113], v[102:103], 1, s[0:1]
	global_store_dwordx4 v[112:113], v[150:153], off
	v_lshl_add_u64 v[112:113], v[102:103], 2, s[2:3]
	s_mov_b64 s[0:1], 0
	global_store_dwordx4 v[112:113], v[90:93], off
	global_store_dwordx4 v[112:113], v[126:129], off offset:16

; __device__ __forceinline__ float silu_f(float x) { return x * __builtin_amdgcn_rcpf(1.f + __expf(-x)); }
;     __device__ __forceinline__ void operator()(const f32x4 (&acc)[2][2][4][2], const pg8::Unit& u, int wr, int wc, int fr, int fq) const {
;     ...
;                 for (int m = 0; m < 4; ++m) rs[ai][m] = rsqrtf(ssq[lrow0 + ai * 128 + m * 16] * (1.f / 1024.f) + EPS);
; #pragma unroll
;             for (int bj = 0; bj < 2; ++bj) {
;                 const int c = c0 + bj * 128;
;                 float lb[8] = {0.f, 0.f, 0.f, 0.f, 0.f, 0.f, 0.f, 0.f};
;                 if (region == 1 && idx != 0) {
;                     const f32x4 a00 = *(const f32x4*)(lbsrc + c), a01 = *(const f32x4*)(lbsrc + c + 4), a10 = *(const f32x4*)(lbsrc + 1024 + c), a11 = *(const f32x4*)(lbsrc + 1024 + c + 4);
; #pragma unroll
;                     for (int j = 0; j < 4; ++j) { lb[j] = __builtin_amdgcn_rcpf(1.f + __expf(a00[j] - a10[j])); lb[4 + j] = __builtin_amdgcn_rcpf(1.f + __expf(a01[j] - a11[j])); }
;                 }
; #pragma unroll
;                 for (int ai = 0; ai < 2; ++ai)
; #pragma unroll
;                     for (int m = 0; m < 4; ++m) {
;                         const int row = lrow0 + ai * 128 + m * 16; const size_t off = (size_t)row * 1024 + c;
;                         const f32x4 v0 = acc[ai][bj][m][0] * rs[ai][m], v1 = acc[ai][bj][m][1] * rs[ai][m];
;                         const float v[8] = {v0[0], v0[1], v0[2], v0[3], v1[0], v1[1], v1[2], v1[3]};
;                         float y[8];
;                         if (region == 0) {
; #pragma unroll
;                             for (int j = 0; j < 8; ++j) y[j] = silu_f(v[j]);
;                             *(v4u*)(o0 + off) = pack8(y);
;                         } else if (region == 1) {
;                             float lf[8];
; #pragma unroll
;                             for (int j = 0; j < 8; ++j) {
;                                 const float om = 1.f - lb[j];
;                                 const float fc = fminf(fmaxf(v[j], -80.f), 80.f);
;                                 const float e = __expf(-fc), sg = __builtin_amdgcn_rcpf(1.f + e);
;                                 y[j] = om * e * sg;
;                                 lf[j] = __logf(fmaxf(lb[j] + om * sg, 1e-30f));
;                             }
;                             *(v4u*)(o1 + off) = pack8(y);
.LBB0_973:
	s_nop 1
	v_fmamk_f32 v90, v201, 0x3a800000, v139
	s_mov_b64 s[0:1], 0x24000
	s_nop 0
	v_rsq_f32_e32 v92, v90
	v_lshlrev_b64 v[90:91], 10, v[178:179]
	v_lshl_add_u64 v[90:91], v[90:91], 0, s[0:1]
	v_or_b32_e32 v94, v90, v198
	s_nop 0
	v_mov_b32_e32 v95, v91
	v_pk_mul_f32 v[96:97], v[88:89], v[92:93] op_sel_hi:[1,0]
	v_pk_mul_f32 v[102:103], v[86:87], v[92:93] op_sel_hi:[1,0]
	v_pk_mul_f32 v[86:87], v[84:85], v[92:93] op_sel_hi:[1,0]
	v_pk_mul_f32 v[88:89], v[82:83], v[92:93] op_sel_hi:[1,0]
	s_and_b64 vcc, exec, s[44:45]
	s_mov_b64 s[0:1], -1
	s_cbranch_vccnz .LBB0_982
	s_and_b64 vcc, exec, s[42:43]
	s_cbranch_vccnz .LBB0_976
	v_max_f32_e32 v82, v102, v102
	s_mov_b32 s39, 0xc2a00000
	v_med3_f32 v82, v82, s39, v195
	v_mul_f32_e32 v82, 0xbfb8aa3b, v82
	v_exp_f32_e32 v82, v82
	v_pk_add_f32 v[110:111], v[176:177], 1.0 op_sel_hi:[1,0] neg_lo:[1,0] neg_hi:[1,0]
	s_mov_b32 s13, 0x3f317217
	s_mov_b32 s15, 0x7f800000
	v_add_f32_e32 v83, 1.0, v82
	v_rcp_f32_e32 v84, v83
	v_max_f32_e32 v83, v103, v103
	v_med3_f32 v83, v83, s39, v195
	v_mul_f32_e32 v83, 0xbfb8aa3b, v83
	v_exp_f32_e32 v83, v83
	v_pk_add_f32 v[118:119], v[174:175], 1.0 op_sel_hi:[1,0] neg_lo:[1,0] neg_hi:[1,0]
	v_pk_add_f32 v[120:121], v[172:173], 1.0 op_sel_hi:[1,0] neg_lo:[1,0] neg_hi:[1,0]
	v_pk_add_f32 v[128:129], v[170:171], 1.0 op_sel_hi:[1,0] neg_lo:[1,0] neg_hi:[1,0]
	v_add_f32_e32 v85, 1.0, v83
	v_rcp_f32_e32 v85, v85
	v_pk_mul_f32 v[82:83], v[82:83], v[110:111]
	s_nop 0
	v_pk_mul_f32 v[104:105], v[84:85], v[82:83]
	v_fma_f32 v82, v84, v110, v176
	v_max_f32_e32 v82, 0xda24260, v82
	v_log_f32_e32 v82, v82
	s_nop 0
	v_mul_f32_e32 v83, 0x3f317217, v82
	v_fma_f32 v83, v82, s13, -v83
	v_fmac_f32_e32 v83, 0x3377d1cf, v82
	v_fmac_f32_e32 v83, 0x3f317217, v82
	v_mov_b32_e32 v82, v83
	v_fma_f32 v83, v85, v111, v177
	v_max_f32_e32 v83, 0xda24260, v83
	v_log_f32_e32 v83, v83
	s_nop 0
	v_mul_f32_e32 v84, 0x3f317217, v83
	v_fma_f32 v84, v83, s13, -v84
	v_fmac_f32_e32 v84, 0x3377d1cf, v83
	v_fmac_f32_e32 v84, 0x3f317217, v83
	v_mov_b32_e32 v83, v84
	v_max_f32_e32 v84, v96, v96
	v_med3_f32 v84, v84, s39, v195
	v_mul_f32_e32 v84, 0xbfb8aa3b, v84
	v_exp_f32_e32 v84, v84
	s_nop 0
	v_add_f32_e32 v85, 1.0, v84
	v_rcp_f32_e32 v112, v85
	v_max_f32_e32 v85, v97, v97
	v_med3_f32 v85, v85, s39, v195
	v_mul_f32_e32 v85, 0xbfb8aa3b, v85
	v_exp_f32_e32 v85, v85
	s_nop 0
	v_add_f32_e32 v93, 1.0, v85
	v_rcp_f32_e32 v113, v93
	v_pk_mul_f32 v[84:85], v[84:85], v[118:119]
	s_nop 0
	v_pk_mul_f32 v[110:111], v[112:113], v[84:85]
	v_fma_f32 v84, v112, v118, v174
	v_max_f32_e32 v84, 0xda24260, v84
	v_log_f32_e32 v84, v84
	s_nop 0
	v_mul_f32_e32 v85, 0x3f317217, v84
	v_fma_f32 v85, v84, s13, -v85
	v_fmac_f32_e32 v85, 0x3377d1cf, v84
	v_fmac_f32_e32 v85, 0x3f317217, v84
	v_mov_b32_e32 v84, v85
	v_fma_f32 v85, v113, v119, v175
	v_max_f32_e32 v85, 0xda24260, v85
	v_log_f32_e32 v85, v85
	s_nop 0
	v_mul_f32_e32 v93, 0x3f317217, v85
	v_fma_f32 v93, v85, s13, -v93
	v_fmac_f32_e32 v93, 0x3377d1cf, v85
	v_fmac_f32_e32 v93, 0x3f317217, v85
	v_mov_b32_e32 v85, v93
	v_max_f32_e32 v93, v88, v88
	v_med3_f32 v93, v93, s39, v195
	v_mul_f32_e32 v93, 0xbfb8aa3b, v93
	v_exp_f32_e32 v112, v93
	s_nop 0
	v_add_f32_e32 v93, 1.0, v112
	v_rcp_f32_e32 v118, v93
	v_max_f32_e32 v93, v89, v89
	v_med3_f32 v93, v93, s39, v195
	v_mul_f32_e32 v93, 0xbfb8aa3b, v93
	v_exp_f32_e32 v113, v93
	s_nop 0
	v_add_f32_e32 v93, 1.0, v113
	v_rcp_f32_e32 v119, v93
	v_fma_f32 v93, v118, v120, v172
	v_max_f32_e32 v93, 0xda24260, v93
	v_pk_mul_f32 v[112:113], v[112:113], v[120:121]
	s_nop 0
	v_log_f32_e32 v93, v93
	v_pk_mul_f32 v[112:113], v[118:119], v[112:113]
	v_mul_f32_e32 v101, 0x3f317217, v93
	v_fma_f32 v101, v93, s13, -v101
	v_fmac_f32_e32 v101, 0x3377d1cf, v93
	v_fmac_f32_e32 v101, 0x3f317217, v93
	v_mov_b32_e32 v93, v101
	v_mov_b32_e32 v118, v93
	v_fma_f32 v93, v119, v121, v173
	v_max_f32_e32 v93, 0xda24260, v93
	v_log_f32_e32 v93, v93
	s_nop 0
	v_mul_f32_e32 v101, 0x3f317217, v93
	v_fma_f32 v101, v93, s13, -v101
	v_fmac_f32_e32 v101, 0x3377d1cf, v93
	v_fmac_f32_e32 v101, 0x3f317217, v93
	v_mov_b32_e32 v93, v101
	v_mov_b32_e32 v119, v93
	v_max_f32_e32 v93, v86, v86
	v_med3_f32 v93, v93, s39, v195
	v_mul_f32_e32 v93, 0xbfb8aa3b, v93
	v_exp_f32_e32 v120, v93
	s_nop 0
	v_add_f32_e32 v93, 1.0, v120
	v_rcp_f32_e32 v126, v93
	v_max_f32_e32 v93, v87, v87
	v_med3_f32 v93, v93, s39, v195
	v_mul_f32_e32 v93, 0xbfb8aa3b, v93
	v_exp_f32_e32 v121, v93
	s_nop 0
	v_add_f32_e32 v93, 1.0, v121
	v_rcp_f32_e32 v127, v93
	v_fma_f32 v93, v126, v128, v170
	v_max_f32_e32 v93, 0xda24260, v93
	v_pk_mul_f32 v[120:121], v[120:121], v[128:129]
	v_cvt_pk_bf16_f32 v128, v112, v113
	v_log_f32_e32 v93, v93
	v_pk_mul_f32 v[150:151], v[126:127], v[120:121]
	v_cvt_pk_bf16_f32 v126, v104, v105
	v_mul_f32_e32 v101, 0x3f317217, v93
	v_fma_f32 v101, v93, s13, -v101
	v_fmac_f32_e32 v101, 0x3377d1cf, v93
	v_fmac_f32_e32 v101, 0x3f317217, v93
	v_mov_b32_e32 v93, v101
	v_mov_b32_e32 v120, v93
	v_fma_f32 v93, v127, v129, v171
	v_max_f32_e32 v93, 0xda24260, v93
	v_cvt_pk_bf16_f32 v127, v110, v111
	v_cvt_pk_bf16_f32 v129, v150, v151
	v_log_f32_e32 v93, v93
	s_nop 0
	v_mul_f32_e32 v101, 0x3f317217, v93
	v_fma_f32 v101, v93, s13, -v101
	v_fmac_f32_e32 v101, 0x3377d1cf, v93
	v_fmac_f32_e32 v101, 0x3f317217, v93
	v_mov_b32_e32 v93, v101
	v_readlane_b32 s0, v253, 0
	v_readlane_b32 s1, v253, 1
	v_mov_b32_e32 v121, v93
	v_lshl_add_u64 v[104:105], v[94:95], 1, s[0:1]
	global_store_dwordx4 v[104:105], v[126:129], off
	v_lshl_add_u64 v[104:105], v[94:95], 2, s[2:3]
	s_mov_b64 s[0:1], 0
	global_store_dwordx4 v[104:105], v[82:85], off
	global_store_dwordx4 v[104:105], v[118:121], off offset:16

; __device__ __forceinline__ float silu_f(float x) { return x * __builtin_amdgcn_rcpf(1.f + __expf(-x)); }
;     __device__ __forceinline__ void operator()(const f32x4 (&acc)[2][2][4][2], const pg8::Unit& u, int wr, int wc, int fr, int fq) const {
;     ...
;                 for (int m = 0; m < 4; ++m) rs[ai][m] = rsqrtf(ssq[lrow0 + ai * 128 + m * 16] * (1.f / 1024.f) + EPS);
; #pragma unroll
;             for (int bj = 0; bj < 2; ++bj) {
;                 const int c = c0 + bj * 128;
;                 float lb[8] = {0.f, 0.f, 0.f, 0.f, 0.f, 0.f, 0.f, 0.f};
;                 if (region == 1 && idx != 0) {
;                     const f32x4 a00 = *(const f32x4*)(lbsrc + c), a01 = *(const f32x4*)(lbsrc + c + 4), a10 = *(const f32x4*)(lbsrc + 1024 + c), a11 = *(const f32x4*)(lbsrc + 1024 + c + 4);
; #pragma unroll
;                     for (int j = 0; j < 4; ++j) { lb[j] = __builtin_amdgcn_rcpf(1.f + __expf(a00[j] - a10[j])); lb[4 + j] = __builtin_amdgcn_rcpf(1.f + __expf(a01[j] - a11[j])); }
;                 }
; #pragma unroll
;                 for (int ai = 0; ai < 2; ++ai)
; #pragma unroll
;                     for (int m = 0; m < 4; ++m) {
;                         const int row = lrow0 + ai * 128 + m * 16; const size_t off = (size_t)row * 1024 + c;
;                         const f32x4 v0 = acc[ai][bj][m][0] * rs[ai][m], v1 = acc[ai][bj][m][1] * rs[ai][m];
;                         const float v[8] = {v0[0], v0[1], v0[2], v0[3], v1[0], v1[1], v1[2], v1[3]};
;                         float y[8];
;                         if (region == 0) {
; #pragma unroll
;                             for (int j = 0; j < 8; ++j) y[j] = silu_f(v[j]);
;                             *(v4u*)(o0 + off) = pack8(y);
;                         } else if (region == 1) {
;                             float lf[8];
; #pragma unroll
;                             for (int j = 0; j < 8; ++j) {
;                                 const float om = 1.f - lb[j];
;                                 const float fc = fminf(fmaxf(v[j], -80.f), 80.f);
;                                 const float e = __expf(-fc), sg = __builtin_amdgcn_rcpf(1.f + e);
;                                 y[j] = om * e * sg;
;                                 lf[j] = __logf(fmaxf(lb[j] + om * sg, 1e-30f));
;                             }
;                             *(v4u*)(o1 + off) = pack8(y);
.LBB0_984:
	s_nop 1
	v_fmamk_f32 v82, v200, 0x3a800000, v139
	s_mov_b64 s[0:1], 0x28000
	s_nop 0
	v_rsq_f32_e32 v84, v82
	v_lshlrev_b64 v[82:83], 10, v[178:179]
	v_lshl_add_u64 v[82:83], v[82:83], 0, s[0:1]
	v_or_b32_e32 v86, v82, v198
	s_nop 0
	v_mov_b32_e32 v87, v83
	v_pk_mul_f32 v[88:89], v[80:81], v[84:85] op_sel_hi:[1,0]
	v_pk_mul_f32 v[94:95], v[78:79], v[84:85] op_sel_hi:[1,0]
	v_pk_mul_f32 v[78:79], v[76:77], v[84:85] op_sel_hi:[1,0]
	v_pk_mul_f32 v[80:81], v[74:75], v[84:85] op_sel_hi:[1,0]
	s_and_b64 vcc, exec, s[44:45]
	s_mov_b64 s[0:1], -1
	s_cbranch_vccnz .LBB0_993
	s_and_b64 vcc, exec, s[42:43]
	s_cbranch_vccnz .LBB0_987
	v_max_f32_e32 v74, v94, v94
	s_mov_b32 s39, 0xc2a00000
	v_med3_f32 v74, v74, s39, v195
	v_mul_f32_e32 v74, 0xbfb8aa3b, v74
	v_exp_f32_e32 v74, v74
	v_pk_add_f32 v[102:103], v[176:177], 1.0 op_sel_hi:[1,0] neg_lo:[1,0] neg_hi:[1,0]
	s_mov_b32 s13, 0x3f317217
	s_mov_b32 s15, 0x7f800000
	v_add_f32_e32 v75, 1.0, v74
	v_rcp_f32_e32 v76, v75
	v_max_f32_e32 v75, v95, v95
	v_med3_f32 v75, v75, s39, v195
	v_mul_f32_e32 v75, 0xbfb8aa3b, v75
	v_exp_f32_e32 v75, v75
	v_pk_add_f32 v[110:111], v[174:175], 1.0 op_sel_hi:[1,0] neg_lo:[1,0] neg_hi:[1,0]
	v_pk_add_f32 v[112:113], v[172:173], 1.0 op_sel_hi:[1,0] neg_lo:[1,0] neg_hi:[1,0]
	v_pk_add_f32 v[120:121], v[170:171], 1.0 op_sel_hi:[1,0] neg_lo:[1,0] neg_hi:[1,0]
	v_add_f32_e32 v77, 1.0, v75
	v_rcp_f32_e32 v77, v77
	v_pk_mul_f32 v[74:75], v[74:75], v[102:103]
	s_nop 0
	v_pk_mul_f32 v[96:97], v[76:77], v[74:75]
	v_fma_f32 v74, v76, v102, v176
	v_max_f32_e32 v74, 0xda24260, v74
	v_log_f32_e32 v74, v74
	s_nop 0
	v_mul_f32_e32 v75, 0x3f317217, v74
	v_fma_f32 v75, v74, s13, -v75
	v_fmac_f32_e32 v75, 0x3377d1cf, v74
	v_fmac_f32_e32 v75, 0x3f317217, v74
	v_mov_b32_e32 v74, v75
	v_fma_f32 v75, v77, v103, v177
	v_max_f32_e32 v75, 0xda24260, v75
	v_log_f32_e32 v75, v75
	s_nop 0
	v_mul_f32_e32 v76, 0x3f317217, v75
	v_fma_f32 v76, v75, s13, -v76
	v_fmac_f32_e32 v76, 0x3377d1cf, v75
	v_fmac_f32_e32 v76, 0x3f317217, v75
	v_mov_b32_e32 v75, v76
	v_max_f32_e32 v76, v88, v88
	v_med3_f32 v76, v76, s39, v195
	v_mul_f32_e32 v76, 0xbfb8aa3b, v76
	v_exp_f32_e32 v76, v76
	s_nop 0
	v_add_f32_e32 v77, 1.0, v76
	v_rcp_f32_e32 v104, v77
	v_max_f32_e32 v77, v89, v89
	v_med3_f32 v77, v77, s39, v195
	v_mul_f32_e32 v77, 0xbfb8aa3b, v77
	v_exp_f32_e32 v77, v77
	s_nop 0
	v_add_f32_e32 v85, 1.0, v77
	v_rcp_f32_e32 v105, v85
	v_pk_mul_f32 v[76:77], v[76:77], v[110:111]
	s_nop 0
	v_pk_mul_f32 v[102:103], v[104:105], v[76:77]
	v_fma_f32 v76, v104, v110, v174
	v_max_f32_e32 v76, 0xda24260, v76
	v_log_f32_e32 v76, v76
	s_nop 0
	v_mul_f32_e32 v77, 0x3f317217, v76
	v_fma_f32 v77, v76, s13, -v77
	v_fmac_f32_e32 v77, 0x3377d1cf, v76
	v_fmac_f32_e32 v77, 0x3f317217, v76
	v_mov_b32_e32 v76, v77
	v_fma_f32 v77, v105, v111, v175
	v_max_f32_e32 v77, 0xda24260, v77
	v_log_f32_e32 v77, v77
	s_nop 0
	v_mul_f32_e32 v85, 0x3f317217, v77
	v_fma_f32 v85, v77, s13, -v85
	v_fmac_f32_e32 v85, 0x3377d1cf, v77
	v_fmac_f32_e32 v85, 0x3f317217, v77
	v_mov_b32_e32 v77, v85
	v_max_f32_e32 v85, v80, v80
	v_med3_f32 v85, v85, s39, v195
	v_mul_f32_e32 v85, 0xbfb8aa3b, v85
	v_exp_f32_e32 v104, v85
	s_nop 0
	v_add_f32_e32 v85, 1.0, v104
	v_rcp_f32_e32 v110, v85
	v_max_f32_e32 v85, v81, v81
	v_med3_f32 v85, v85, s39, v195
	v_mul_f32_e32 v85, 0xbfb8aa3b, v85
	v_exp_f32_e32 v105, v85
	s_nop 0
	v_add_f32_e32 v85, 1.0, v105
	v_rcp_f32_e32 v111, v85
	v_fma_f32 v85, v110, v112, v172
	v_max_f32_e32 v85, 0xda24260, v85
	v_pk_mul_f32 v[104:105], v[104:105], v[112:113]
	s_nop 0
	v_log_f32_e32 v85, v85
	v_pk_mul_f32 v[104:105], v[110:111], v[104:105]
	v_mul_f32_e32 v93, 0x3f317217, v85
	v_fma_f32 v93, v85, s13, -v93
	v_fmac_f32_e32 v93, 0x3377d1cf, v85
	v_fmac_f32_e32 v93, 0x3f317217, v85
	v_mov_b32_e32 v85, v93
	v_mov_b32_e32 v110, v85
	v_fma_f32 v85, v111, v113, v173
	v_max_f32_e32 v85, 0xda24260, v85
	v_log_f32_e32 v85, v85
	s_nop 0
	v_mul_f32_e32 v93, 0x3f317217, v85
	v_fma_f32 v93, v85, s13, -v93
	v_fmac_f32_e32 v93, 0x3377d1cf, v85
	v_fmac_f32_e32 v93, 0x3f317217, v85
	v_mov_b32_e32 v85, v93
	v_mov_b32_e32 v111, v85
	v_max_f32_e32 v85, v78, v78
	v_med3_f32 v85, v85, s39, v195
	v_mul_f32_e32 v85, 0xbfb8aa3b, v85
	v_exp_f32_e32 v112, v85
	s_nop 0
	v_add_f32_e32 v85, 1.0, v112
	v_rcp_f32_e32 v118, v85
	v_max_f32_e32 v85, v79, v79
	v_med3_f32 v85, v85, s39, v195
	v_mul_f32_e32 v85, 0xbfb8aa3b, v85
	v_exp_f32_e32 v113, v85
	s_nop 0
	v_add_f32_e32 v85, 1.0, v113
	v_rcp_f32_e32 v119, v85
	v_fma_f32 v85, v118, v120, v170
	v_max_f32_e32 v85, 0xda24260, v85
	v_pk_mul_f32 v[112:113], v[112:113], v[120:121]
	v_cvt_pk_bf16_f32 v120, v104, v105
	v_log_f32_e32 v85, v85
	v_pk_mul_f32 v[126:127], v[118:119], v[112:113]
	v_cvt_pk_bf16_f32 v118, v96, v97
	v_mul_f32_e32 v93, 0x3f317217, v85
	v_fma_f32 v93, v85, s13, -v93
	v_fmac_f32_e32 v93, 0x3377d1cf, v85
	v_fmac_f32_e32 v93, 0x3f317217, v85
	v_mov_b32_e32 v85, v93
	v_mov_b32_e32 v112, v85
	v_fma_f32 v85, v119, v121, v171
	v_max_f32_e32 v85, 0xda24260, v85
	v_cvt_pk_bf16_f32 v119, v102, v103
	v_cvt_pk_bf16_f32 v121, v126, v127
	v_log_f32_e32 v85, v85
	s_nop 0
	v_mul_f32_e32 v93, 0x3f317217, v85
	v_fma_f32 v93, v85, s13, -v93
	v_fmac_f32_e32 v93, 0x3377d1cf, v85
	v_fmac_f32_e32 v93, 0x3f317217, v85
	v_mov_b32_e32 v85, v93
	v_readlane_b32 s0, v253, 0
	v_readlane_b32 s1, v253, 1
	v_mov_b32_e32 v113, v85
	v_lshl_add_u64 v[96:97], v[86:87], 1, s[0:1]
	global_store_dwordx4 v[96:97], v[118:121], off
	v_lshl_add_u64 v[96:97], v[86:87], 2, s[2:3]
	s_mov_b64 s[0:1], 0
	global_store_dwordx4 v[96:97], v[74:77], off
	global_store_dwordx4 v[96:97], v[110:113], off offset:16

; __device__ __forceinline__ float silu_f(float x) { return x * __builtin_amdgcn_rcpf(1.f + __expf(-x)); }
;     __device__ __forceinline__ void operator()(const f32x4 (&acc)[2][2][4][2], const pg8::Unit& u, int wr, int wc, int fr, int fq) const {
;     ...
;                 for (int m = 0; m < 4; ++m) rs[ai][m] = rsqrtf(ssq[lrow0 + ai * 128 + m * 16] * (1.f / 1024.f) + EPS);
; #pragma unroll
;             for (int bj = 0; bj < 2; ++bj) {
;                 const int c = c0 + bj * 128;
;                 float lb[8] = {0.f, 0.f, 0.f, 0.f, 0.f, 0.f, 0.f, 0.f};
;                 if (region == 1 && idx != 0) {
;                     const f32x4 a00 = *(const f32x4*)(lbsrc + c), a01 = *(const f32x4*)(lbsrc + c + 4), a10 = *(const f32x4*)(lbsrc + 1024 + c), a11 = *(const f32x4*)(lbsrc + 1024 + c + 4);
; #pragma unroll
;                     for (int j = 0; j < 4; ++j) { lb[j] = __builtin_amdgcn_rcpf(1.f + __expf(a00[j] - a10[j])); lb[4 + j] = __builtin_amdgcn_rcpf(1.f + __expf(a01[j] - a11[j])); }
;                 }
; #pragma unroll
;                 for (int ai = 0; ai < 2; ++ai)
; #pragma unroll
;                     for (int m = 0; m < 4; ++m) {
;                         const int row = lrow0 + ai * 128 + m * 16; const size_t off = (size_t)row * 1024 + c;
;                         const f32x4 v0 = acc[ai][bj][m][0] * rs[ai][m], v1 = acc[ai][bj][m][1] * rs[ai][m];
;                         const float v[8] = {v0[0], v0[1], v0[2], v0[3], v1[0], v1[1], v1[2], v1[3]};
;                         float y[8];
;                         if (region == 0) {
; #pragma unroll
;                             for (int j = 0; j < 8; ++j) y[j] = silu_f(v[j]);
;                             *(v4u*)(o0 + off) = pack8(y);
;                         } else if (region == 1) {
;                             float lf[8];
; #pragma unroll
;                             for (int j = 0; j < 8; ++j) {
;                                 const float om = 1.f - lb[j];
;                                 const float fc = fminf(fmaxf(v[j], -80.f), 80.f);
;                                 const float e = __expf(-fc), sg = __builtin_amdgcn_rcpf(1.f + e);
;                                 y[j] = om * e * sg;
;                                 lf[j] = __logf(fmaxf(lb[j] + om * sg, 1e-30f));
;                             }
;                             *(v4u*)(o1 + off) = pack8(y);
.LBB0_995:
	s_nop 1
	v_fmamk_f32 v74, v199, 0x3a800000, v139
	s_mov_b64 s[0:1], 0x2c000
	s_nop 0
	v_rsq_f32_e32 v76, v74
	v_lshlrev_b64 v[74:75], 10, v[178:179]
	v_lshl_add_u64 v[74:75], v[74:75], 0, s[0:1]
	v_or_b32_e32 v78, v74, v198
	s_nop 0
	v_mov_b32_e32 v79, v75
	v_pk_mul_f32 v[80:81], v[72:73], v[76:77] op_sel_hi:[1,0]
	v_pk_mul_f32 v[86:87], v[70:71], v[76:77] op_sel_hi:[1,0]
	v_pk_mul_f32 v[70:71], v[68:69], v[76:77] op_sel_hi:[1,0]
	v_pk_mul_f32 v[72:73], v[66:67], v[76:77] op_sel_hi:[1,0]
	s_and_b64 vcc, exec, s[44:45]
	s_mov_b64 s[0:1], -1
	s_cbranch_vccnz .LBB0_1004
	s_and_b64 vcc, exec, s[42:43]
	s_cbranch_vccnz .LBB0_998
	v_max_f32_e32 v66, v86, v86
	s_mov_b32 s39, 0xc2a00000
	v_med3_f32 v66, v66, s39, v195
	v_mul_f32_e32 v66, 0xbfb8aa3b, v66
	v_exp_f32_e32 v66, v66
	v_pk_add_f32 v[94:95], v[176:177], 1.0 op_sel_hi:[1,0] neg_lo:[1,0] neg_hi:[1,0]
	s_mov_b32 s13, 0x3f317217
	s_mov_b32 s15, 0x7f800000
	v_add_f32_e32 v67, 1.0, v66
	v_rcp_f32_e32 v68, v67
	v_max_f32_e32 v67, v87, v87
	v_med3_f32 v67, v67, s39, v195
	v_mul_f32_e32 v67, 0xbfb8aa3b, v67
	v_exp_f32_e32 v67, v67
	v_fmac_f32_e32 v176, v68, v94
	v_pk_add_f32 v[102:103], v[174:175], 1.0 op_sel_hi:[1,0] neg_lo:[1,0] neg_hi:[1,0]
	v_pk_add_f32 v[104:105], v[172:173], 1.0 op_sel_hi:[1,0] neg_lo:[1,0] neg_hi:[1,0]
	v_add_f32_e32 v69, 1.0, v67
	v_rcp_f32_e32 v69, v69
	v_pk_mul_f32 v[66:67], v[66:67], v[94:95]
	v_pk_add_f32 v[112:113], v[170:171], 1.0 op_sel_hi:[1,0] neg_lo:[1,0] neg_hi:[1,0]
	v_pk_mul_f32 v[88:89], v[68:69], v[66:67]
	v_max_f32_e32 v66, 0xda24260, v176
	v_fmac_f32_e32 v177, v69, v95
	s_nop 0
	v_log_f32_e32 v66, v66
	s_nop 0
	v_mul_f32_e32 v67, 0x3f317217, v66
	v_fma_f32 v67, v66, s13, -v67
	v_fmac_f32_e32 v67, 0x3377d1cf, v66
	v_fmac_f32_e32 v67, 0x3f317217, v66
	v_mov_b32_e32 v66, v67
	v_max_f32_e32 v67, 0xda24260, v177
	v_log_f32_e32 v67, v67
	s_nop 0
	v_mul_f32_e32 v68, 0x3f317217, v67
	v_fma_f32 v68, v67, s13, -v68
	v_fmac_f32_e32 v68, 0x3377d1cf, v67
	v_fmac_f32_e32 v68, 0x3f317217, v67
	v_mov_b32_e32 v67, v68
	v_max_f32_e32 v68, v80, v80
	v_med3_f32 v68, v68, s39, v195
	v_mul_f32_e32 v68, 0xbfb8aa3b, v68
	v_exp_f32_e32 v68, v68
	s_nop 0
	v_add_f32_e32 v69, 1.0, v68
	v_rcp_f32_e32 v96, v69
	v_max_f32_e32 v69, v81, v81
	v_med3_f32 v69, v69, s39, v195
	v_mul_f32_e32 v69, 0xbfb8aa3b, v69
	v_exp_f32_e32 v69, v69
	v_fmac_f32_e32 v174, v96, v102
	v_add_f32_e32 v77, 1.0, v69
	v_rcp_f32_e32 v97, v77
	v_pk_mul_f32 v[68:69], v[68:69], v[102:103]
	v_fmac_f32_e32 v175, v97, v103
	v_pk_mul_f32 v[94:95], v[96:97], v[68:69]
	v_max_f32_e32 v68, 0xda24260, v174
	v_log_f32_e32 v68, v68
	s_nop 0
	v_mul_f32_e32 v69, 0x3f317217, v68
	v_fma_f32 v69, v68, s13, -v69
	v_fmac_f32_e32 v69, 0x3377d1cf, v68
	v_fmac_f32_e32 v69, 0x3f317217, v68
	v_mov_b32_e32 v68, v69
	v_max_f32_e32 v69, 0xda24260, v175
	v_log_f32_e32 v69, v69
	s_nop 0
	v_mul_f32_e32 v77, 0x3f317217, v69
	v_fma_f32 v77, v69, s13, -v77
	v_fmac_f32_e32 v77, 0x3377d1cf, v69
	v_fmac_f32_e32 v77, 0x3f317217, v69
	v_mov_b32_e32 v69, v77
	v_max_f32_e32 v77, v72, v72
	v_med3_f32 v77, v77, s39, v195
	v_mul_f32_e32 v77, 0xbfb8aa3b, v77
	v_exp_f32_e32 v96, v77
	s_nop 0
	v_add_f32_e32 v77, 1.0, v96
	v_rcp_f32_e32 v102, v77
	v_max_f32_e32 v77, v73, v73
	v_med3_f32 v77, v77, s39, v195
	v_mul_f32_e32 v77, 0xbfb8aa3b, v77
	v_exp_f32_e32 v97, v77
	v_fmac_f32_e32 v172, v102, v104
	v_add_f32_e32 v77, 1.0, v97
	v_rcp_f32_e32 v103, v77
	v_max_f32_e32 v77, 0xda24260, v172
	v_pk_mul_f32 v[96:97], v[96:97], v[104:105]
	v_fmac_f32_e32 v173, v103, v105
	v_log_f32_e32 v77, v77
	v_pk_mul_f32 v[96:97], v[102:103], v[96:97]
	v_mul_f32_e32 v85, 0x3f317217, v77
	v_fma_f32 v85, v77, s13, -v85
	v_fmac_f32_e32 v85, 0x3377d1cf, v77
	v_fmac_f32_e32 v85, 0x3f317217, v77
	v_mov_b32_e32 v77, v85
	v_mov_b32_e32 v102, v77
	v_max_f32_e32 v77, 0xda24260, v173
	v_log_f32_e32 v77, v77
	s_nop 0
	v_mul_f32_e32 v85, 0x3f317217, v77
	v_fma_f32 v85, v77, s13, -v85
	v_fmac_f32_e32 v85, 0x3377d1cf, v77
	v_fmac_f32_e32 v85, 0x3f317217, v77
	v_mov_b32_e32 v77, v85
	v_mov_b32_e32 v103, v77
	v_max_f32_e32 v77, v70, v70
	v_med3_f32 v77, v77, s39, v195
	v_mul_f32_e32 v77, 0xbfb8aa3b, v77
	v_exp_f32_e32 v104, v77
	s_nop 0
	v_add_f32_e32 v77, 1.0, v104
	v_rcp_f32_e32 v110, v77
	v_max_f32_e32 v77, v71, v71
	v_med3_f32 v77, v77, s39, v195
	v_mul_f32_e32 v77, 0xbfb8aa3b, v77
	v_exp_f32_e32 v105, v77
	v_fmac_f32_e32 v170, v110, v112
	v_add_f32_e32 v77, 1.0, v105
	v_rcp_f32_e32 v111, v77
	v_max_f32_e32 v77, 0xda24260, v170
	v_pk_mul_f32 v[104:105], v[104:105], v[112:113]
	v_fmac_f32_e32 v171, v111, v113
	v_log_f32_e32 v77, v77
	v_pk_mul_f32 v[118:119], v[110:111], v[104:105]
	v_cvt_pk_bf16_f32 v110, v88, v89
	v_cvt_pk_bf16_f32 v111, v94, v95
	v_mul_f32_e32 v85, 0x3f317217, v77
	v_fma_f32 v85, v77, s13, -v85
	v_fmac_f32_e32 v85, 0x3377d1cf, v77
	v_fmac_f32_e32 v85, 0x3f317217, v77
	v_cvt_pk_bf16_f32 v112, v96, v97
	v_cvt_pk_bf16_f32 v113, v118, v119
	v_mov_b32_e32 v77, v85
	v_mov_b32_e32 v104, v77
	v_max_f32_e32 v77, 0xda24260, v171
	v_log_f32_e32 v77, v77
	s_nop 0
	v_mul_f32_e32 v85, 0x3f317217, v77
	v_fma_f32 v85, v77, s13, -v85
	v_fmac_f32_e32 v85, 0x3377d1cf, v77
	v_fmac_f32_e32 v85, 0x3f317217, v77
	v_mov_b32_e32 v77, v85
	v_readlane_b32 s0, v253, 0
	v_readlane_b32 s1, v253, 1
	v_mov_b32_e32 v105, v77
	v_lshl_add_u64 v[88:89], v[78:79], 1, s[0:1]
	global_store_dwordx4 v[88:89], v[110:113], off
	v_lshl_add_u64 v[88:89], v[78:79], 2, s[2:3]
	s_mov_b64 s[0:1], 0
	global_store_dwordx4 v[88:89], v[66:69], off
	global_store_dwordx4 v[88:89], v[102:105], off offset:16

; __device__ __forceinline__ float silu_f(float x) { return x * __builtin_amdgcn_rcpf(1.f + __expf(-x)); }
; __device__ __forceinline__ v4u pack8(const float (&y)[8]) { return (v4u){pk2(y[0], y[1]), pk2(y[2], y[3]), pk2(y[4], y[5]), pk2(y[6], y[7])}; }
;     __device__ __forceinline__ void operator()(const f32x4 (&acc)[2][2][4][2], const pg8::Unit& u, int wr, int wc, int fr, int fq) const {
;     ...
;                         const int row = lrow0 + ai * 128 + m * 16; const size_t off = (size_t)row * 1024 + c;
;                         const f32x4 v0 = acc[ai][bj][m][0] * rs[ai][m], v1 = acc[ai][bj][m][1] * rs[ai][m];
;                         const float v[8] = {v0[0], v0[1], v0[2], v0[3], v1[0], v1[1], v1[2], v1[3]};
;                         float y[8];
;                         if (region == 0) {
; #pragma unroll
;                             for (int j = 0; j < 8; ++j) y[j] = silu_f(v[j]);
;                             *(v4u*)(o0 + off) = pack8(y);
;                         } else if (region == 1) {
;                             float lf[8];
; #pragma unroll
;                             for (int j = 0; j < 8; ++j) {
;                                 const float om = 1.f - lb[j];
;                                 const float fc = fminf(fmaxf(v[j], -80.f), 80.f);
;                                 const float e = __expf(-fc), sg = __builtin_amdgcn_rcpf(1.f + e);
;                                 y[j] = om * e * sg;
;                                 lf[j] = __logf(fmaxf(lb[j] + om * sg, 1e-30f));
;                             }
;                             *(v4u*)(o1 + off) = pack8(y);
;                             *(f32x4*)(of + off) = (f32x4){lf[0], lf[1], lf[2], lf[3]}; *(f32x4*)(of + off + 4) = (f32x4){lf[4], lf[5], lf[6], lf[7]};
.LBB0_1008:
	v_mov_b32_e32 v169, v168
	v_mov_b32_e32 v86, v168
	v_mov_b32_e32 v87, v168
	v_or_b32_e32 v166, v166, v94
	v_pk_mul_f32 v[78:79], v[64:65], v[86:87]
	v_pk_mul_f32 v[80:81], v[62:63], v[168:169]
	v_pk_mul_f32 v[62:63], v[60:61], v[86:87]
	v_pk_mul_f32 v[64:65], v[58:59], v[168:169]
	s_and_b64 vcc, exec, s[44:45]
	s_mov_b64 s[0:1], -1
	s_cbranch_vccnz .LBB0_1017
	s_and_b64 vcc, exec, s[42:43]
	s_cbranch_vccnz .LBB0_1011
	v_max_f32_e32 v58, v80, v80
	s_mov_b32 s28, 0xc2a00000
	v_med3_f32 v58, v58, s28, v195
	v_mul_f32_e32 v58, 0xbfb8aa3b, v58
	v_exp_f32_e32 v58, v58
	v_pk_add_f32 v[88:89], v[72:73], 1.0 op_sel_hi:[1,0] neg_lo:[1,0] neg_hi:[1,0]
	s_mov_b32 s13, 0x3f317217
	s_mov_b32 s15, 0x7f800000
	v_add_f32_e32 v59, 1.0, v58
	v_rcp_f32_e32 v60, v59
	v_max_f32_e32 v59, v81, v81
	v_med3_f32 v59, v59, s28, v195
	v_mul_f32_e32 v59, 0xbfb8aa3b, v59
	v_exp_f32_e32 v59, v59
	v_pk_add_f32 v[102:103], v[70:71], 1.0 op_sel_hi:[1,0] neg_lo:[1,0] neg_hi:[1,0]
	v_pk_add_f32 v[104:105], v[68:69], 1.0 op_sel_hi:[1,0] neg_lo:[1,0] neg_hi:[1,0]
	v_pk_add_f32 v[112:113], v[66:67], 1.0 op_sel_hi:[1,0] neg_lo:[1,0] neg_hi:[1,0]
	v_add_f32_e32 v61, 1.0, v59
	v_rcp_f32_e32 v61, v61
	v_pk_mul_f32 v[58:59], v[58:59], v[88:89]
	s_nop 0
	v_pk_mul_f32 v[86:87], v[60:61], v[58:59]
	v_fma_f32 v58, v60, v88, v72
	v_max_f32_e32 v58, 0xda24260, v58
	v_cvt_pk_bf16_f32 v86, v86, v87
	s_nop 0
	v_log_f32_e32 v58, v58
	s_nop 0
	v_mul_f32_e32 v59, 0x3f317217, v58
	v_fma_f32 v59, v58, s13, -v59
	v_fmac_f32_e32 v59, 0x3377d1cf, v58
	v_fmac_f32_e32 v59, 0x3f317217, v58
	v_mov_b32_e32 v58, v59
	v_fma_f32 v59, v61, v89, v73
	v_max_f32_e32 v59, 0xda24260, v59
	v_log_f32_e32 v59, v59
	s_nop 0
	v_mul_f32_e32 v60, 0x3f317217, v59
	v_fma_f32 v60, v59, s13, -v60
	v_fmac_f32_e32 v60, 0x3377d1cf, v59
	v_fmac_f32_e32 v60, 0x3f317217, v59
	v_mov_b32_e32 v59, v60
	v_max_f32_e32 v60, v78, v78
	v_med3_f32 v60, v60, s28, v195
	v_mul_f32_e32 v60, 0xbfb8aa3b, v60
	v_exp_f32_e32 v60, v60
	s_nop 0
	v_add_f32_e32 v61, 1.0, v60
	v_rcp_f32_e32 v96, v61
	v_max_f32_e32 v61, v79, v79
	v_med3_f32 v61, v61, s28, v195
	v_mul_f32_e32 v61, 0xbfb8aa3b, v61
	v_exp_f32_e32 v61, v61
	s_nop 0
	v_add_f32_e32 v77, 1.0, v61
	v_rcp_f32_e32 v97, v77
	v_pk_mul_f32 v[60:61], v[60:61], v[102:103]
	s_nop 0
	v_pk_mul_f32 v[88:89], v[96:97], v[60:61]
	v_fma_f32 v60, v96, v102, v70
	v_max_f32_e32 v60, 0xda24260, v60
	v_cvt_pk_bf16_f32 v87, v88, v89
	s_nop 0
	v_log_f32_e32 v60, v60
	s_nop 0
	v_mul_f32_e32 v61, 0x3f317217, v60
	v_fma_f32 v61, v60, s13, -v61
	v_fmac_f32_e32 v61, 0x3377d1cf, v60
	v_fmac_f32_e32 v61, 0x3f317217, v60
	v_mov_b32_e32 v60, v61
	v_fma_f32 v61, v97, v103, v71
	v_max_f32_e32 v61, 0xda24260, v61
	v_log_f32_e32 v61, v61
	s_nop 0
	v_mul_f32_e32 v77, 0x3f317217, v61
	v_fma_f32 v77, v61, s13, -v77
	v_fmac_f32_e32 v77, 0x3377d1cf, v61
	v_fmac_f32_e32 v77, 0x3f317217, v61
	v_mov_b32_e32 v61, v77
	v_max_f32_e32 v77, v64, v64
	v_med3_f32 v77, v77, s28, v195
	v_mul_f32_e32 v77, 0xbfb8aa3b, v77
	v_exp_f32_e32 v96, v77
	s_nop 0
	v_add_f32_e32 v77, 1.0, v96
	v_rcp_f32_e32 v102, v77
	v_max_f32_e32 v77, v65, v65
	v_med3_f32 v77, v77, s28, v195
	v_mul_f32_e32 v77, 0xbfb8aa3b, v77
	v_exp_f32_e32 v97, v77
	s_nop 0
	v_add_f32_e32 v77, 1.0, v97
	v_rcp_f32_e32 v103, v77
	v_fma_f32 v77, v102, v104, v68
	v_max_f32_e32 v77, 0xda24260, v77
	v_pk_mul_f32 v[96:97], v[96:97], v[104:105]
	s_nop 0
	v_log_f32_e32 v77, v77
	v_pk_mul_f32 v[96:97], v[102:103], v[96:97]
	v_mul_f32_e32 v85, 0x3f317217, v77
	v_fma_f32 v85, v77, s13, -v85
	v_fmac_f32_e32 v85, 0x3377d1cf, v77
	v_fmac_f32_e32 v85, 0x3f317217, v77
	v_cvt_pk_bf16_f32 v88, v96, v97
	s_nop 0
	v_mov_b32_e32 v77, v85
	v_mov_b32_e32 v102, v77
	v_fma_f32 v77, v103, v105, v69
	v_max_f32_e32 v77, 0xda24260, v77
	v_log_f32_e32 v77, v77
	s_nop 0
	v_mul_f32_e32 v85, 0x3f317217, v77
	v_fma_f32 v85, v77, s13, -v85
	v_fmac_f32_e32 v85, 0x3377d1cf, v77
	v_fmac_f32_e32 v85, 0x3f317217, v77
	v_mov_b32_e32 v77, v85
	v_mov_b32_e32 v103, v77
	v_max_f32_e32 v77, v62, v62
	v_med3_f32 v77, v77, s28, v195
	v_mul_f32_e32 v77, 0xbfb8aa3b, v77
	v_exp_f32_e32 v104, v77
	s_nop 0
	v_add_f32_e32 v77, 1.0, v104
	v_rcp_f32_e32 v110, v77
	v_max_f32_e32 v77, v63, v63
	v_med3_f32 v77, v77, s28, v195
	v_mul_f32_e32 v77, 0xbfb8aa3b, v77
	v_exp_f32_e32 v105, v77
	s_nop 0
	v_add_f32_e32 v77, 1.0, v105
	v_rcp_f32_e32 v111, v77
	v_fma_f32 v77, v110, v112, v66
	v_max_f32_e32 v77, 0xda24260, v77
	v_pk_mul_f32 v[104:105], v[104:105], v[112:113]
	s_nop 0
	v_log_f32_e32 v77, v77
	v_pk_mul_f32 v[118:119], v[110:111], v[104:105]
	v_mul_f32_e32 v85, 0x3f317217, v77
	v_fma_f32 v85, v77, s13, -v85
	v_fmac_f32_e32 v85, 0x3377d1cf, v77
	v_fmac_f32_e32 v85, 0x3f317217, v77
	v_cvt_pk_bf16_f32 v89, v118, v119
	s_nop 0
	v_mov_b32_e32 v77, v85
	v_mov_b32_e32 v104, v77
	v_fma_f32 v77, v111, v113, v67
	v_max_f32_e32 v77, 0xda24260, v77
	v_log_f32_e32 v77, v77
	s_nop 0
	v_mul_f32_e32 v85, 0x3f317217, v77
	v_fma_f32 v85, v77, s13, -v85
	v_fmac_f32_e32 v85, 0x3377d1cf, v77
	v_fmac_f32_e32 v85, 0x3f317217, v77
	v_mov_b32_e32 v77, v85
	v_readlane_b32 s0, v253, 0
	v_readlane_b32 s1, v253, 1
	v_mov_b32_e32 v105, v77
	v_lshl_add_u64 v[96:97], v[166:167], 1, s[0:1]
	global_store_dwordx4 v[96:97], v[86:89], off
	s_mov_b64 s[0:1], 0
	s_nop 0
	v_lshl_add_u64 v[86:87], v[166:167], 2, s[2:3]
	global_store_dwordx4 v[86:87], v[58:61], off
	global_store_dwordx4 v[86:87], v[102:105], off offset:16

; __device__ __forceinline__ float silu_f(float x) { return x * __builtin_amdgcn_rcpf(1.f + __expf(-x)); }
; __device__ __forceinline__ v4u pack8(const float (&y)[8]) { return (v4u){pk2(y[0], y[1]), pk2(y[2], y[3]), pk2(y[4], y[5]), pk2(y[6], y[7])}; }
;     __device__ __forceinline__ void operator()(const f32x4 (&acc)[2][2][4][2], const pg8::Unit& u, int wr, int wc, int fr, int fq) const {
;     ...
;                         const int row = lrow0 + ai * 128 + m * 16; const size_t off = (size_t)row * 1024 + c;
;                         const f32x4 v0 = acc[ai][bj][m][0] * rs[ai][m], v1 = acc[ai][bj][m][1] * rs[ai][m];
;                         const float v[8] = {v0[0], v0[1], v0[2], v0[3], v1[0], v1[1], v1[2], v1[3]};
;                         float y[8];
;                         if (region == 0) {
; #pragma unroll
;                             for (int j = 0; j < 8; ++j) y[j] = silu_f(v[j]);
;                             *(v4u*)(o0 + off) = pack8(y);
;                         } else if (region == 1) {
;                             float lf[8];
; #pragma unroll
;                             for (int j = 0; j < 8; ++j) {
;                                 const float om = 1.f - lb[j];
;                                 const float fc = fminf(fmaxf(v[j], -80.f), 80.f);
;                                 const float e = __expf(-fc), sg = __builtin_amdgcn_rcpf(1.f + e);
;                                 y[j] = om * e * sg;
;                                 lf[j] = __logf(fmaxf(lb[j] + om * sg, 1e-30f));
;                             }
;                             *(v4u*)(o1 + off) = pack8(y);
;                             *(f32x4*)(of + off) = (f32x4){lf[0], lf[1], lf[2], lf[3]}; *(f32x4*)(of + off + 4) = (f32x4){lf[4], lf[5], lf[6], lf[7]};
.LBB0_1019:
	v_mov_b32_e32 v125, v124
	v_mov_b32_e32 v62, v124
	v_mov_b32_e32 v63, v124
	v_or_b32_e32 v122, v122, v94
	v_pk_mul_f32 v[58:59], v[56:57], v[62:63]
	v_pk_mul_f32 v[60:61], v[54:55], v[124:125]
	v_pk_mul_f32 v[54:55], v[52:53], v[62:63]
	v_pk_mul_f32 v[56:57], v[50:51], v[124:125]
	s_and_b64 vcc, exec, s[44:45]
	s_mov_b64 s[0:1], -1
	s_cbranch_vccnz .LBB0_1028
	s_and_b64 vcc, exec, s[42:43]
	s_cbranch_vccnz .LBB0_1022
	v_max_f32_e32 v50, v60, v60
	s_mov_b32 s28, 0xc2a00000
	v_med3_f32 v50, v50, s28, v195
	v_mul_f32_e32 v50, 0xbfb8aa3b, v50
	v_exp_f32_e32 v50, v50
	v_pk_add_f32 v[64:65], v[72:73], 1.0 op_sel_hi:[1,0] neg_lo:[1,0] neg_hi:[1,0]
	s_mov_b32 s13, 0x3f317217
	s_mov_b32 s15, 0x7f800000
	v_add_f32_e32 v51, 1.0, v50
	v_rcp_f32_e32 v52, v51
	v_max_f32_e32 v51, v61, v61
	v_med3_f32 v51, v51, s28, v195
	v_mul_f32_e32 v51, 0xbfb8aa3b, v51
	v_exp_f32_e32 v51, v51
	v_pk_add_f32 v[80:81], v[70:71], 1.0 op_sel_hi:[1,0] neg_lo:[1,0] neg_hi:[1,0]
	v_pk_add_f32 v[86:87], v[68:69], 1.0 op_sel_hi:[1,0] neg_lo:[1,0] neg_hi:[1,0]
	v_pk_add_f32 v[96:97], v[66:67], 1.0 op_sel_hi:[1,0] neg_lo:[1,0] neg_hi:[1,0]
	v_add_f32_e32 v53, 1.0, v51
	v_rcp_f32_e32 v53, v53
	v_pk_mul_f32 v[50:51], v[50:51], v[64:65]
	s_nop 0
	v_pk_mul_f32 v[62:63], v[52:53], v[50:51]
	v_fma_f32 v50, v52, v64, v72
	v_max_f32_e32 v50, 0xda24260, v50
	v_cvt_pk_bf16_f32 v62, v62, v63
	s_nop 0
	v_log_f32_e32 v50, v50
	s_nop 0
	v_mul_f32_e32 v51, 0x3f317217, v50
	v_fma_f32 v51, v50, s13, -v51
	v_fmac_f32_e32 v51, 0x3377d1cf, v50
	v_fmac_f32_e32 v51, 0x3f317217, v50
	v_mov_b32_e32 v50, v51
	v_fma_f32 v51, v53, v65, v73
	v_max_f32_e32 v51, 0xda24260, v51
	v_log_f32_e32 v51, v51
	s_nop 0
	v_mul_f32_e32 v52, 0x3f317217, v51
	v_fma_f32 v52, v51, s13, -v52
	v_fmac_f32_e32 v52, 0x3377d1cf, v51
	v_fmac_f32_e32 v52, 0x3f317217, v51
	v_mov_b32_e32 v51, v52
	v_max_f32_e32 v52, v58, v58
	v_med3_f32 v52, v52, s28, v195
	v_mul_f32_e32 v52, 0xbfb8aa3b, v52
	v_exp_f32_e32 v52, v52
	s_nop 0
	v_add_f32_e32 v53, 1.0, v52
	v_rcp_f32_e32 v78, v53
	v_max_f32_e32 v53, v59, v59
	v_med3_f32 v53, v53, s28, v195
	v_mul_f32_e32 v53, 0xbfb8aa3b, v53
	v_exp_f32_e32 v53, v53
	s_nop 0
	v_add_f32_e32 v64, 1.0, v53
	v_rcp_f32_e32 v79, v64
	v_pk_mul_f32 v[52:53], v[52:53], v[80:81]
	s_nop 0
	v_pk_mul_f32 v[64:65], v[78:79], v[52:53]
	v_fma_f32 v52, v78, v80, v70
	v_max_f32_e32 v52, 0xda24260, v52
	v_cvt_pk_bf16_f32 v63, v64, v65
	s_nop 0
	v_log_f32_e32 v52, v52
	s_nop 0
	v_mul_f32_e32 v53, 0x3f317217, v52
	v_fma_f32 v53, v52, s13, -v53
	v_fmac_f32_e32 v53, 0x3377d1cf, v52
	v_fmac_f32_e32 v53, 0x3f317217, v52
	v_mov_b32_e32 v52, v53
	v_fma_f32 v53, v79, v81, v71
	v_max_f32_e32 v53, 0xda24260, v53
	v_log_f32_e32 v53, v53
	s_nop 0
	v_mul_f32_e32 v77, 0x3f317217, v53
	v_fma_f32 v77, v53, s13, -v77
	v_fmac_f32_e32 v77, 0x3377d1cf, v53
	v_fmac_f32_e32 v77, 0x3f317217, v53
	v_mov_b32_e32 v53, v77
	v_max_f32_e32 v77, v56, v56
	v_med3_f32 v77, v77, s28, v195
	v_mul_f32_e32 v77, 0xbfb8aa3b, v77
	v_exp_f32_e32 v78, v77
	s_nop 0
	v_add_f32_e32 v77, 1.0, v78
	v_rcp_f32_e32 v80, v77
	v_max_f32_e32 v77, v57, v57
	v_med3_f32 v77, v77, s28, v195
	v_mul_f32_e32 v77, 0xbfb8aa3b, v77
	v_exp_f32_e32 v79, v77
	s_nop 0
	v_add_f32_e32 v77, 1.0, v79
	v_rcp_f32_e32 v81, v77
	v_fma_f32 v77, v80, v86, v68
	v_max_f32_e32 v77, 0xda24260, v77
	v_pk_mul_f32 v[78:79], v[78:79], v[86:87]
	v_pk_mul_f32 v[88:89], v[80:81], v[78:79]
	s_nop 0
	v_log_f32_e32 v77, v77
	v_cvt_pk_bf16_f32 v64, v88, v89
	v_mul_f32_e32 v78, 0x3f317217, v77
	v_fma_f32 v78, v77, s13, -v78
	v_fmac_f32_e32 v78, 0x3377d1cf, v77
	v_fmac_f32_e32 v78, 0x3f317217, v77
	v_mov_b32_e32 v77, v78
	v_mov_b32_e32 v78, v77
	v_fma_f32 v77, v81, v87, v69
	v_max_f32_e32 v77, 0xda24260, v77
	v_log_f32_e32 v77, v77
	s_nop 0
	v_mul_f32_e32 v79, 0x3f317217, v77
	v_fma_f32 v79, v77, s13, -v79
	v_fmac_f32_e32 v79, 0x3377d1cf, v77
	v_fmac_f32_e32 v79, 0x3f317217, v77
	v_mov_b32_e32 v77, v79
	v_mov_b32_e32 v79, v77
	v_max_f32_e32 v77, v54, v54
	v_med3_f32 v77, v77, s28, v195
	v_mul_f32_e32 v77, 0xbfb8aa3b, v77
	v_exp_f32_e32 v80, v77
	s_nop 0
	v_add_f32_e32 v77, 1.0, v80
	v_rcp_f32_e32 v86, v77
	v_max_f32_e32 v77, v55, v55
	v_med3_f32 v77, v77, s28, v195
	v_mul_f32_e32 v77, 0xbfb8aa3b, v77
	v_exp_f32_e32 v81, v77
	s_nop 0
	v_add_f32_e32 v77, 1.0, v81
	v_rcp_f32_e32 v87, v77
	v_fma_f32 v77, v86, v96, v66
	v_max_f32_e32 v77, 0xda24260, v77
	v_pk_mul_f32 v[80:81], v[80:81], v[96:97]
	v_pk_mul_f32 v[102:103], v[86:87], v[80:81]
	s_nop 0
	v_log_f32_e32 v77, v77
	v_cvt_pk_bf16_f32 v65, v102, v103
	v_mul_f32_e32 v80, 0x3f317217, v77
	v_fma_f32 v80, v77, s13, -v80
	v_fmac_f32_e32 v80, 0x3377d1cf, v77
	v_fmac_f32_e32 v80, 0x3f317217, v77
	v_mov_b32_e32 v77, v80
	v_mov_b32_e32 v80, v77
	v_fma_f32 v77, v87, v97, v67
	v_max_f32_e32 v77, 0xda24260, v77
	v_log_f32_e32 v77, v77
	s_nop 0
	v_mul_f32_e32 v81, 0x3f317217, v77
	v_fma_f32 v81, v77, s13, -v81
	v_fmac_f32_e32 v81, 0x3377d1cf, v77
	v_fmac_f32_e32 v81, 0x3f317217, v77
	v_mov_b32_e32 v77, v81
	v_readlane_b32 s0, v253, 0
	v_readlane_b32 s1, v253, 1
	v_mov_b32_e32 v81, v77
	v_lshl_add_u64 v[86:87], v[122:123], 1, s[0:1]
	global_store_dwordx4 v[86:87], v[62:65], off
	s_mov_b64 s[0:1], 0
	s_nop 0
	v_lshl_add_u64 v[62:63], v[122:123], 2, s[2:3]
	global_store_dwordx4 v[62:63], v[50:53], off
	global_store_dwordx4 v[62:63], v[78:81], off offset:16

; __device__ __forceinline__ float silu_f(float x) { return x * __builtin_amdgcn_rcpf(1.f + __expf(-x)); }
; __device__ __forceinline__ v4u pack8(const float (&y)[8]) { return (v4u){pk2(y[0], y[1]), pk2(y[2], y[3]), pk2(y[4], y[5]), pk2(y[6], y[7])}; }
;     __device__ __forceinline__ void operator()(const f32x4 (&acc)[2][2][4][2], const pg8::Unit& u, int wr, int wc, int fr, int fq) const {
;     ...
;                         const int row = lrow0 + ai * 128 + m * 16; const size_t off = (size_t)row * 1024 + c;
;                         const f32x4 v0 = acc[ai][bj][m][0] * rs[ai][m], v1 = acc[ai][bj][m][1] * rs[ai][m];
;                         const float v[8] = {v0[0], v0[1], v0[2], v0[3], v1[0], v1[1], v1[2], v1[3]};
;                         float y[8];
;                         if (region == 0) {
; #pragma unroll
;                             for (int j = 0; j < 8; ++j) y[j] = silu_f(v[j]);
;                             *(v4u*)(o0 + off) = pack8(y);
;                         } else if (region == 1) {
;                             float lf[8];
; #pragma unroll
;                             for (int j = 0; j < 8; ++j) {
;                                 const float om = 1.f - lb[j];
;                                 const float fc = fminf(fmaxf(v[j], -80.f), 80.f);
;                                 const float e = __expf(-fc), sg = __builtin_amdgcn_rcpf(1.f + e);
;                                 y[j] = om * e * sg;
;                                 lf[j] = __logf(fmaxf(lb[j] + om * sg, 1e-30f));
;                             }
;                             *(v4u*)(o1 + off) = pack8(y);
;                             *(f32x4*)(of + off) = (f32x4){lf[0], lf[1], lf[2], lf[3]}; *(f32x4*)(of + off + 4) = (f32x4){lf[4], lf[5], lf[6], lf[7]};
.LBB0_1030:
	v_mov_b32_e32 v117, v116
	v_mov_b32_e32 v54, v116
	v_mov_b32_e32 v55, v116
	v_or_b32_e32 v114, v114, v94
	v_pk_mul_f32 v[50:51], v[48:49], v[54:55]
	v_pk_mul_f32 v[52:53], v[46:47], v[116:117]
	v_pk_mul_f32 v[46:47], v[44:45], v[54:55]
	v_pk_mul_f32 v[48:49], v[42:43], v[116:117]
	s_and_b64 vcc, exec, s[44:45]
	s_mov_b64 s[0:1], -1
	s_cbranch_vccnz .LBB0_1039
	s_and_b64 vcc, exec, s[42:43]
	s_cbranch_vccnz .LBB0_1033
	v_max_f32_e32 v42, v52, v52
	s_mov_b32 s28, 0xc2a00000
	v_med3_f32 v42, v42, s28, v195
	v_mul_f32_e32 v42, 0xbfb8aa3b, v42
	v_exp_f32_e32 v42, v42
	v_pk_add_f32 v[56:57], v[72:73], 1.0 op_sel_hi:[1,0] neg_lo:[1,0] neg_hi:[1,0]
	s_mov_b32 s13, 0x3f317217
	s_mov_b32 s15, 0x7f800000
	v_add_f32_e32 v43, 1.0, v42
	v_rcp_f32_e32 v44, v43
	v_max_f32_e32 v43, v53, v53
	v_med3_f32 v43, v43, s28, v195
	v_mul_f32_e32 v43, 0xbfb8aa3b, v43
	v_exp_f32_e32 v43, v43
	v_pk_add_f32 v[60:61], v[70:71], 1.0 op_sel_hi:[1,0] neg_lo:[1,0] neg_hi:[1,0]
	v_pk_add_f32 v[62:63], v[68:69], 1.0 op_sel_hi:[1,0] neg_lo:[1,0] neg_hi:[1,0]
	v_pk_add_f32 v[78:79], v[66:67], 1.0 op_sel_hi:[1,0] neg_lo:[1,0] neg_hi:[1,0]
	v_add_f32_e32 v45, 1.0, v43
	v_rcp_f32_e32 v45, v45
	v_pk_mul_f32 v[42:43], v[42:43], v[56:57]
	s_nop 0
	v_pk_mul_f32 v[54:55], v[44:45], v[42:43]
	v_fma_f32 v42, v44, v56, v72
	v_max_f32_e32 v42, 0xda24260, v42
	v_cvt_pk_bf16_f32 v54, v54, v55
	s_nop 0
	v_log_f32_e32 v42, v42
	s_nop 0
	v_mul_f32_e32 v43, 0x3f317217, v42
	v_fma_f32 v43, v42, s13, -v43
	v_fmac_f32_e32 v43, 0x3377d1cf, v42
	v_fmac_f32_e32 v43, 0x3f317217, v42
	v_mov_b32_e32 v42, v43
	v_fma_f32 v43, v45, v57, v73
	v_max_f32_e32 v43, 0xda24260, v43
	v_log_f32_e32 v43, v43
	s_nop 0
	v_mul_f32_e32 v44, 0x3f317217, v43
	v_fma_f32 v44, v43, s13, -v44
	v_fmac_f32_e32 v44, 0x3377d1cf, v43
	v_fmac_f32_e32 v44, 0x3f317217, v43
	v_mov_b32_e32 v43, v44
	v_max_f32_e32 v44, v50, v50
	v_med3_f32 v44, v44, s28, v195
	v_mul_f32_e32 v44, 0xbfb8aa3b, v44
	v_exp_f32_e32 v44, v44
	s_nop 0
	v_add_f32_e32 v45, 1.0, v44
	v_rcp_f32_e32 v58, v45
	v_max_f32_e32 v45, v51, v51
	v_med3_f32 v45, v45, s28, v195
	v_mul_f32_e32 v45, 0xbfb8aa3b, v45
	v_exp_f32_e32 v45, v45
	s_nop 0
	v_add_f32_e32 v56, 1.0, v45
	v_rcp_f32_e32 v59, v56
	v_pk_mul_f32 v[44:45], v[44:45], v[60:61]
	s_nop 0
	v_pk_mul_f32 v[56:57], v[58:59], v[44:45]
	v_fma_f32 v44, v58, v60, v70
	v_max_f32_e32 v44, 0xda24260, v44
	v_cvt_pk_bf16_f32 v55, v56, v57
	s_nop 0
	v_log_f32_e32 v44, v44
	s_nop 0
	v_mul_f32_e32 v45, 0x3f317217, v44
	v_fma_f32 v45, v44, s13, -v45
	v_fmac_f32_e32 v45, 0x3377d1cf, v44
	v_fmac_f32_e32 v45, 0x3f317217, v44
	v_mov_b32_e32 v44, v45
	v_fma_f32 v45, v59, v61, v71
	v_max_f32_e32 v45, 0xda24260, v45
	v_log_f32_e32 v45, v45
	s_nop 0
	v_mul_f32_e32 v58, 0x3f317217, v45
	v_fma_f32 v58, v45, s13, -v58
	v_fmac_f32_e32 v58, 0x3377d1cf, v45
	v_fmac_f32_e32 v58, 0x3f317217, v45
	v_mov_b32_e32 v45, v58
	v_max_f32_e32 v58, v48, v48
	v_med3_f32 v58, v58, s28, v195
	v_mul_f32_e32 v58, 0xbfb8aa3b, v58
	v_exp_f32_e32 v58, v58
	s_nop 0
	v_add_f32_e32 v59, 1.0, v58
	v_rcp_f32_e32 v60, v59
	v_max_f32_e32 v59, v49, v49
	v_med3_f32 v59, v59, s28, v195
	v_mul_f32_e32 v59, 0xbfb8aa3b, v59
	v_exp_f32_e32 v59, v59
	s_nop 0
	v_add_f32_e32 v61, 1.0, v59
	v_rcp_f32_e32 v61, v61
	v_pk_mul_f32 v[58:59], v[58:59], v[62:63]
	s_nop 0
	v_pk_mul_f32 v[64:65], v[60:61], v[58:59]
	v_fma_f32 v58, v60, v62, v68
	v_max_f32_e32 v58, 0xda24260, v58
	v_cvt_pk_bf16_f32 v56, v64, v65
	s_nop 0
	v_log_f32_e32 v58, v58
	s_nop 0
	v_mul_f32_e32 v59, 0x3f317217, v58
	v_fma_f32 v59, v58, s13, -v59
	v_fmac_f32_e32 v59, 0x3377d1cf, v58
	v_fmac_f32_e32 v59, 0x3f317217, v58
	v_mov_b32_e32 v58, v59
	v_fma_f32 v59, v61, v63, v69
	v_max_f32_e32 v59, 0xda24260, v59
	v_log_f32_e32 v59, v59
	s_nop 0
	v_mul_f32_e32 v60, 0x3f317217, v59
	v_fma_f32 v60, v59, s13, -v60
	v_fmac_f32_e32 v60, 0x3377d1cf, v59
	v_fmac_f32_e32 v60, 0x3f317217, v59
	v_mov_b32_e32 v59, v60
	v_max_f32_e32 v60, v46, v46
	v_med3_f32 v60, v60, s28, v195
	v_mul_f32_e32 v60, 0xbfb8aa3b, v60
	v_exp_f32_e32 v60, v60
	s_nop 0
	v_add_f32_e32 v61, 1.0, v60
	v_rcp_f32_e32 v62, v61
	v_max_f32_e32 v61, v47, v47
	v_med3_f32 v61, v61, s28, v195
	v_mul_f32_e32 v61, 0xbfb8aa3b, v61
	v_exp_f32_e32 v61, v61
	s_nop 0
	v_add_f32_e32 v63, 1.0, v61
	v_rcp_f32_e32 v63, v63
	v_pk_mul_f32 v[60:61], v[60:61], v[78:79]
	s_nop 0
	v_pk_mul_f32 v[80:81], v[62:63], v[60:61]
	v_fma_f32 v60, v62, v78, v66
	v_max_f32_e32 v60, 0xda24260, v60
	v_cvt_pk_bf16_f32 v57, v80, v81
	s_nop 0
	v_log_f32_e32 v60, v60
	s_nop 0
	v_mul_f32_e32 v61, 0x3f317217, v60
	v_fma_f32 v61, v60, s13, -v61
	v_fmac_f32_e32 v61, 0x3377d1cf, v60
	v_fmac_f32_e32 v61, 0x3f317217, v60
	v_mov_b32_e32 v60, v61
	v_fma_f32 v61, v63, v79, v67
	v_max_f32_e32 v61, 0xda24260, v61
	v_log_f32_e32 v61, v61
	s_nop 0
	v_mul_f32_e32 v62, 0x3f317217, v61
	v_fma_f32 v62, v61, s13, -v62
	v_fmac_f32_e32 v62, 0x3377d1cf, v61
	v_fmac_f32_e32 v62, 0x3f317217, v61
	v_mov_b32_e32 v61, v62
	v_readlane_b32 s0, v253, 0
	v_readlane_b32 s1, v253, 1
	s_nop 0
	v_lshl_add_u64 v[62:63], v[114:115], 1, s[0:1]
	global_store_dwordx4 v[62:63], v[54:57], off
	s_mov_b64 s[0:1], 0
	s_nop 0
	v_lshl_add_u64 v[54:55], v[114:115], 2, s[2:3]
	global_store_dwordx4 v[54:55], v[42:45], off
	global_store_dwordx4 v[54:55], v[58:61], off offset:16

; __device__ __forceinline__ float silu_f(float x) { return x * __builtin_amdgcn_rcpf(1.f + __expf(-x)); }
; __device__ __forceinline__ v4u pack8(const float (&y)[8]) { return (v4u){pk2(y[0], y[1]), pk2(y[2], y[3]), pk2(y[4], y[5]), pk2(y[6], y[7])}; }
;     __device__ __forceinline__ void operator()(const f32x4 (&acc)[2][2][4][2], const pg8::Unit& u, int wr, int wc, int fr, int fq) const {
;     ...
;                         const int row = lrow0 + ai * 128 + m * 16; const size_t off = (size_t)row * 1024 + c;
;                         const f32x4 v0 = acc[ai][bj][m][0] * rs[ai][m], v1 = acc[ai][bj][m][1] * rs[ai][m];
;                         const float v[8] = {v0[0], v0[1], v0[2], v0[3], v1[0], v1[1], v1[2], v1[3]};
;                         float y[8];
;                         if (region == 0) {
; #pragma unroll
;                             for (int j = 0; j < 8; ++j) y[j] = silu_f(v[j]);
;                             *(v4u*)(o0 + off) = pack8(y);
;                         } else if (region == 1) {
;                             float lf[8];
; #pragma unroll
;                             for (int j = 0; j < 8; ++j) {
;                                 const float om = 1.f - lb[j];
;                                 const float fc = fminf(fmaxf(v[j], -80.f), 80.f);
;                                 const float e = __expf(-fc), sg = __builtin_amdgcn_rcpf(1.f + e);
;                                 y[j] = om * e * sg;
;                                 lf[j] = __logf(fmaxf(lb[j] + om * sg, 1e-30f));
;                             }
;                             *(v4u*)(o1 + off) = pack8(y);
;                             *(f32x4*)(of + off) = (f32x4){lf[0], lf[1], lf[2], lf[3]}; *(f32x4*)(of + off + 4) = (f32x4){lf[4], lf[5], lf[6], lf[7]};
.LBB0_1041:
	v_mov_b32_e32 v109, v108
	v_mov_b32_e32 v46, v108
	v_mov_b32_e32 v47, v108
	v_or_b32_e32 v106, v106, v94
	v_pk_mul_f32 v[42:43], v[40:41], v[46:47]
	v_pk_mul_f32 v[44:45], v[38:39], v[108:109]
	v_pk_mul_f32 v[38:39], v[36:37], v[46:47]
	v_pk_mul_f32 v[40:41], v[34:35], v[108:109]
	s_and_b64 vcc, exec, s[44:45]
	s_mov_b64 s[0:1], -1
	s_cbranch_vccnz .LBB0_1050
	s_and_b64 vcc, exec, s[42:43]
	s_cbranch_vccnz .LBB0_1044
	v_max_f32_e32 v34, v44, v44
	s_mov_b32 s28, 0xc2a00000
	v_med3_f32 v34, v34, s28, v195
	v_mul_f32_e32 v34, 0xbfb8aa3b, v34
	v_exp_f32_e32 v34, v34
	v_pk_add_f32 v[48:49], v[72:73], 1.0 op_sel_hi:[1,0] neg_lo:[1,0] neg_hi:[1,0]
	s_mov_b32 s13, 0x3f317217
	s_mov_b32 s15, 0x7f800000
	v_add_f32_e32 v35, 1.0, v34
	v_rcp_f32_e32 v36, v35
	v_max_f32_e32 v35, v45, v45
	v_med3_f32 v35, v35, s28, v195
	v_mul_f32_e32 v35, 0xbfb8aa3b, v35
	v_exp_f32_e32 v35, v35
	v_pk_add_f32 v[52:53], v[70:71], 1.0 op_sel_hi:[1,0] neg_lo:[1,0] neg_hi:[1,0]
	v_pk_add_f32 v[54:55], v[68:69], 1.0 op_sel_hi:[1,0] neg_lo:[1,0] neg_hi:[1,0]
	v_pk_add_f32 v[58:59], v[66:67], 1.0 op_sel_hi:[1,0] neg_lo:[1,0] neg_hi:[1,0]
	v_add_f32_e32 v37, 1.0, v35
	v_rcp_f32_e32 v37, v37
	v_pk_mul_f32 v[34:35], v[34:35], v[48:49]
	s_nop 0
	v_pk_mul_f32 v[46:47], v[36:37], v[34:35]
	v_fma_f32 v34, v36, v48, v72
	v_max_f32_e32 v34, 0xda24260, v34
	v_cvt_pk_bf16_f32 v46, v46, v47
	s_nop 0
	v_log_f32_e32 v34, v34
	s_nop 0
	v_mul_f32_e32 v35, 0x3f317217, v34
	v_fma_f32 v35, v34, s13, -v35
	v_fmac_f32_e32 v35, 0x3377d1cf, v34
	v_fmac_f32_e32 v35, 0x3f317217, v34
	v_mov_b32_e32 v34, v35
	v_fma_f32 v35, v37, v49, v73
	v_max_f32_e32 v35, 0xda24260, v35
	v_log_f32_e32 v35, v35
	s_nop 0
	v_mul_f32_e32 v36, 0x3f317217, v35
	v_fma_f32 v36, v35, s13, -v36
	v_fmac_f32_e32 v36, 0x3377d1cf, v35
	v_fmac_f32_e32 v36, 0x3f317217, v35
	v_mov_b32_e32 v35, v36
	v_max_f32_e32 v36, v42, v42
	v_med3_f32 v36, v36, s28, v195
	v_mul_f32_e32 v36, 0xbfb8aa3b, v36
	v_exp_f32_e32 v36, v36
	s_nop 0
	v_add_f32_e32 v37, 1.0, v36
	v_rcp_f32_e32 v50, v37
	v_max_f32_e32 v37, v43, v43
	v_med3_f32 v37, v37, s28, v195
	v_mul_f32_e32 v37, 0xbfb8aa3b, v37
	v_exp_f32_e32 v37, v37
	s_nop 0
	v_add_f32_e32 v48, 1.0, v37
	v_rcp_f32_e32 v51, v48
	v_pk_mul_f32 v[36:37], v[36:37], v[52:53]
	s_nop 0
	v_pk_mul_f32 v[48:49], v[50:51], v[36:37]
	v_fma_f32 v36, v50, v52, v70
	v_max_f32_e32 v36, 0xda24260, v36
	v_cvt_pk_bf16_f32 v47, v48, v49
	s_nop 0
	v_log_f32_e32 v36, v36
	s_nop 0
	v_mul_f32_e32 v37, 0x3f317217, v36
	v_fma_f32 v37, v36, s13, -v37
	v_fmac_f32_e32 v37, 0x3377d1cf, v36
	v_fmac_f32_e32 v37, 0x3f317217, v36
	v_mov_b32_e32 v36, v37
	v_fma_f32 v37, v51, v53, v71
	v_max_f32_e32 v37, 0xda24260, v37
	v_log_f32_e32 v37, v37
	s_nop 0
	v_mul_f32_e32 v50, 0x3f317217, v37
	v_fma_f32 v50, v37, s13, -v50
	v_fmac_f32_e32 v50, 0x3377d1cf, v37
	v_fmac_f32_e32 v50, 0x3f317217, v37
	v_mov_b32_e32 v37, v50
	v_max_f32_e32 v50, v40, v40
	v_med3_f32 v50, v50, s28, v195
	v_mul_f32_e32 v50, 0xbfb8aa3b, v50
	v_exp_f32_e32 v50, v50
	s_nop 0
	v_add_f32_e32 v51, 1.0, v50
	v_rcp_f32_e32 v52, v51
	v_max_f32_e32 v51, v41, v41
	v_med3_f32 v51, v51, s28, v195
	v_mul_f32_e32 v51, 0xbfb8aa3b, v51
	v_exp_f32_e32 v51, v51
	s_nop 0
	v_add_f32_e32 v53, 1.0, v51
	v_rcp_f32_e32 v53, v53
	v_pk_mul_f32 v[50:51], v[50:51], v[54:55]
	s_nop 0
	v_pk_mul_f32 v[56:57], v[52:53], v[50:51]
	v_fma_f32 v50, v52, v54, v68
	v_max_f32_e32 v50, 0xda24260, v50
	v_cvt_pk_bf16_f32 v48, v56, v57
	s_nop 0
	v_log_f32_e32 v50, v50
	s_nop 0
	v_mul_f32_e32 v51, 0x3f317217, v50
	v_fma_f32 v51, v50, s13, -v51
	v_fmac_f32_e32 v51, 0x3377d1cf, v50
	v_fmac_f32_e32 v51, 0x3f317217, v50
	v_mov_b32_e32 v50, v51
	v_fma_f32 v51, v53, v55, v69
	v_max_f32_e32 v51, 0xda24260, v51
	v_log_f32_e32 v51, v51
	s_nop 0
	v_mul_f32_e32 v52, 0x3f317217, v51
	v_fma_f32 v52, v51, s13, -v52
	v_fmac_f32_e32 v52, 0x3377d1cf, v51
	v_fmac_f32_e32 v52, 0x3f317217, v51
	v_mov_b32_e32 v51, v52
	v_max_f32_e32 v52, v38, v38
	v_med3_f32 v52, v52, s28, v195
	v_mul_f32_e32 v52, 0xbfb8aa3b, v52
	v_exp_f32_e32 v52, v52
	s_nop 0
	v_add_f32_e32 v53, 1.0, v52
	v_rcp_f32_e32 v54, v53
	v_max_f32_e32 v53, v39, v39
	v_med3_f32 v53, v53, s28, v195
	v_mul_f32_e32 v53, 0xbfb8aa3b, v53
	v_exp_f32_e32 v53, v53
	s_nop 0
	v_add_f32_e32 v55, 1.0, v53
	v_rcp_f32_e32 v55, v55
	v_pk_mul_f32 v[52:53], v[52:53], v[58:59]
	s_nop 0
	v_pk_mul_f32 v[60:61], v[54:55], v[52:53]
	v_fma_f32 v52, v54, v58, v66
	v_max_f32_e32 v52, 0xda24260, v52
	v_cvt_pk_bf16_f32 v49, v60, v61
	s_nop 0
	v_log_f32_e32 v52, v52
	s_nop 0
	v_mul_f32_e32 v53, 0x3f317217, v52
	v_fma_f32 v53, v52, s13, -v53
	v_fmac_f32_e32 v53, 0x3377d1cf, v52
	v_fmac_f32_e32 v53, 0x3f317217, v52
	v_mov_b32_e32 v52, v53
	v_fma_f32 v53, v55, v59, v67
	v_max_f32_e32 v53, 0xda24260, v53
	v_log_f32_e32 v53, v53
	s_nop 0
	v_mul_f32_e32 v54, 0x3f317217, v53
	v_fma_f32 v54, v53, s13, -v54
	v_fmac_f32_e32 v54, 0x3377d1cf, v53
	v_fmac_f32_e32 v54, 0x3f317217, v53
	v_mov_b32_e32 v53, v54
	v_readlane_b32 s0, v253, 0
	v_readlane_b32 s1, v253, 1
	s_nop 0
	v_lshl_add_u64 v[54:55], v[106:107], 1, s[0:1]
	global_store_dwordx4 v[54:55], v[46:49], off
	s_mov_b64 s[0:1], 0
	s_nop 0
	v_lshl_add_u64 v[46:47], v[106:107], 2, s[2:3]
	global_store_dwordx4 v[46:47], v[34:37], off
	global_store_dwordx4 v[46:47], v[50:53], off offset:16

; __device__ __forceinline__ float silu_f(float x) { return x * __builtin_amdgcn_rcpf(1.f + __expf(-x)); }
; __device__ __forceinline__ v4u pack8(const float (&y)[8]) { return (v4u){pk2(y[0], y[1]), pk2(y[2], y[3]), pk2(y[4], y[5]), pk2(y[6], y[7])}; }
;     __device__ __forceinline__ void operator()(const f32x4 (&acc)[2][2][4][2], const pg8::Unit& u, int wr, int wc, int fr, int fq) const {
;     ...
;                         const int row = lrow0 + ai * 128 + m * 16; const size_t off = (size_t)row * 1024 + c;
;                         const f32x4 v0 = acc[ai][bj][m][0] * rs[ai][m], v1 = acc[ai][bj][m][1] * rs[ai][m];
;                         const float v[8] = {v0[0], v0[1], v0[2], v0[3], v1[0], v1[1], v1[2], v1[3]};
;                         float y[8];
;                         if (region == 0) {
; #pragma unroll
;                             for (int j = 0; j < 8; ++j) y[j] = silu_f(v[j]);
;                             *(v4u*)(o0 + off) = pack8(y);
;                         } else if (region == 1) {
;                             float lf[8];
; #pragma unroll
;                             for (int j = 0; j < 8; ++j) {
;                                 const float om = 1.f - lb[j];
;                                 const float fc = fminf(fmaxf(v[j], -80.f), 80.f);
;                                 const float e = __expf(-fc), sg = __builtin_amdgcn_rcpf(1.f + e);
;                                 y[j] = om * e * sg;
;                                 lf[j] = __logf(fmaxf(lb[j] + om * sg, 1e-30f));
;                             }
;                             *(v4u*)(o1 + off) = pack8(y);
;                             *(f32x4*)(of + off) = (f32x4){lf[0], lf[1], lf[2], lf[3]}; *(f32x4*)(of + off + 4) = (f32x4){lf[4], lf[5], lf[6], lf[7]};
.LBB0_1052:
	v_mov_b32_e32 v101, v100
	v_mov_b32_e32 v38, v100
	v_mov_b32_e32 v39, v100
	v_or_b32_e32 v98, v98, v94
	v_pk_mul_f32 v[34:35], v[32:33], v[38:39]
	v_pk_mul_f32 v[36:37], v[30:31], v[100:101]
	v_pk_mul_f32 v[30:31], v[28:29], v[38:39]
	v_pk_mul_f32 v[32:33], v[26:27], v[100:101]
	s_and_b64 vcc, exec, s[44:45]
	s_mov_b64 s[0:1], -1
	s_cbranch_vccnz .LBB0_1061
	s_and_b64 vcc, exec, s[42:43]
	s_cbranch_vccnz .LBB0_1055
	v_max_f32_e32 v26, v36, v36
	s_mov_b32 s28, 0xc2a00000
	v_med3_f32 v26, v26, s28, v195
	v_mul_f32_e32 v26, 0xbfb8aa3b, v26
	v_exp_f32_e32 v26, v26
	v_pk_add_f32 v[40:41], v[72:73], 1.0 op_sel_hi:[1,0] neg_lo:[1,0] neg_hi:[1,0]
	s_mov_b32 s13, 0x3f317217
	s_mov_b32 s15, 0x7f800000
	v_add_f32_e32 v27, 1.0, v26
	v_rcp_f32_e32 v28, v27
	v_max_f32_e32 v27, v37, v37
	v_med3_f32 v27, v27, s28, v195
	v_mul_f32_e32 v27, 0xbfb8aa3b, v27
	v_exp_f32_e32 v27, v27
	v_pk_add_f32 v[44:45], v[70:71], 1.0 op_sel_hi:[1,0] neg_lo:[1,0] neg_hi:[1,0]
	v_pk_add_f32 v[46:47], v[68:69], 1.0 op_sel_hi:[1,0] neg_lo:[1,0] neg_hi:[1,0]
	v_pk_add_f32 v[50:51], v[66:67], 1.0 op_sel_hi:[1,0] neg_lo:[1,0] neg_hi:[1,0]
	v_add_f32_e32 v29, 1.0, v27
	v_rcp_f32_e32 v29, v29
	v_pk_mul_f32 v[26:27], v[26:27], v[40:41]
	s_nop 0
	v_pk_mul_f32 v[38:39], v[28:29], v[26:27]
	v_fma_f32 v26, v28, v40, v72
	v_max_f32_e32 v26, 0xda24260, v26
	v_cvt_pk_bf16_f32 v38, v38, v39
	s_nop 0
	v_log_f32_e32 v26, v26
	s_nop 0
	v_mul_f32_e32 v27, 0x3f317217, v26
	v_fma_f32 v27, v26, s13, -v27
	v_fmac_f32_e32 v27, 0x3377d1cf, v26
	v_fmac_f32_e32 v27, 0x3f317217, v26
	v_mov_b32_e32 v26, v27
	v_fma_f32 v27, v29, v41, v73
	v_max_f32_e32 v27, 0xda24260, v27
	v_log_f32_e32 v27, v27
	s_nop 0
	v_mul_f32_e32 v28, 0x3f317217, v27
	v_fma_f32 v28, v27, s13, -v28
	v_fmac_f32_e32 v28, 0x3377d1cf, v27
	v_fmac_f32_e32 v28, 0x3f317217, v27
	v_mov_b32_e32 v27, v28
	v_max_f32_e32 v28, v34, v34
	v_med3_f32 v28, v28, s28, v195
	v_mul_f32_e32 v28, 0xbfb8aa3b, v28
	v_exp_f32_e32 v28, v28
	s_nop 0
	v_add_f32_e32 v29, 1.0, v28
	v_rcp_f32_e32 v42, v29
	v_max_f32_e32 v29, v35, v35
	v_med3_f32 v29, v29, s28, v195
	v_mul_f32_e32 v29, 0xbfb8aa3b, v29
	v_exp_f32_e32 v29, v29
	s_nop 0
	v_add_f32_e32 v40, 1.0, v29
	v_rcp_f32_e32 v43, v40
	v_pk_mul_f32 v[28:29], v[28:29], v[44:45]
	s_nop 0
	v_pk_mul_f32 v[40:41], v[42:43], v[28:29]
	v_fma_f32 v28, v42, v44, v70
	v_max_f32_e32 v28, 0xda24260, v28
	v_cvt_pk_bf16_f32 v39, v40, v41
	s_nop 0
	v_log_f32_e32 v28, v28
	s_nop 0
	v_mul_f32_e32 v29, 0x3f317217, v28
	v_fma_f32 v29, v28, s13, -v29
	v_fmac_f32_e32 v29, 0x3377d1cf, v28
	v_fmac_f32_e32 v29, 0x3f317217, v28
	v_mov_b32_e32 v28, v29
	v_fma_f32 v29, v43, v45, v71
	v_max_f32_e32 v29, 0xda24260, v29
	v_log_f32_e32 v29, v29
	s_nop 0
	v_mul_f32_e32 v42, 0x3f317217, v29
	v_fma_f32 v42, v29, s13, -v42
	v_fmac_f32_e32 v42, 0x3377d1cf, v29
	v_fmac_f32_e32 v42, 0x3f317217, v29
	v_mov_b32_e32 v29, v42
	v_max_f32_e32 v42, v32, v32
	v_med3_f32 v42, v42, s28, v195
	v_mul_f32_e32 v42, 0xbfb8aa3b, v42
	v_exp_f32_e32 v42, v42
	s_nop 0
	v_add_f32_e32 v43, 1.0, v42
	v_rcp_f32_e32 v44, v43
	v_max_f32_e32 v43, v33, v33
	v_med3_f32 v43, v43, s28, v195
	v_mul_f32_e32 v43, 0xbfb8aa3b, v43
	v_exp_f32_e32 v43, v43
	s_nop 0
	v_add_f32_e32 v45, 1.0, v43
	v_rcp_f32_e32 v45, v45
	v_pk_mul_f32 v[42:43], v[42:43], v[46:47]
	s_nop 0
	v_pk_mul_f32 v[48:49], v[44:45], v[42:43]
	v_fma_f32 v42, v44, v46, v68
	v_max_f32_e32 v42, 0xda24260, v42
	v_cvt_pk_bf16_f32 v40, v48, v49
	s_nop 0
	v_log_f32_e32 v42, v42
	s_nop 0
	v_mul_f32_e32 v43, 0x3f317217, v42
	v_fma_f32 v43, v42, s13, -v43
	v_fmac_f32_e32 v43, 0x3377d1cf, v42
	v_fmac_f32_e32 v43, 0x3f317217, v42
	v_mov_b32_e32 v42, v43
	v_fma_f32 v43, v45, v47, v69
	v_max_f32_e32 v43, 0xda24260, v43
	v_log_f32_e32 v43, v43
	s_nop 0
	v_mul_f32_e32 v44, 0x3f317217, v43
	v_fma_f32 v44, v43, s13, -v44
	v_fmac_f32_e32 v44, 0x3377d1cf, v43
	v_fmac_f32_e32 v44, 0x3f317217, v43
	v_mov_b32_e32 v43, v44
	v_max_f32_e32 v44, v30, v30
	v_med3_f32 v44, v44, s28, v195
	v_mul_f32_e32 v44, 0xbfb8aa3b, v44
	v_exp_f32_e32 v44, v44
	s_nop 0
	v_add_f32_e32 v45, 1.0, v44
	v_rcp_f32_e32 v46, v45
	v_max_f32_e32 v45, v31, v31
	v_med3_f32 v45, v45, s28, v195
	v_mul_f32_e32 v45, 0xbfb8aa3b, v45
	v_exp_f32_e32 v45, v45
	s_nop 0
	v_add_f32_e32 v47, 1.0, v45
	v_rcp_f32_e32 v47, v47
	v_pk_mul_f32 v[44:45], v[44:45], v[50:51]
	s_nop 0
	v_pk_mul_f32 v[52:53], v[46:47], v[44:45]
	v_fma_f32 v44, v46, v50, v66
	v_max_f32_e32 v44, 0xda24260, v44
	v_cvt_pk_bf16_f32 v41, v52, v53
	s_nop 0
	v_log_f32_e32 v44, v44
	s_nop 0
	v_mul_f32_e32 v45, 0x3f317217, v44
	v_fma_f32 v45, v44, s13, -v45
	v_fmac_f32_e32 v45, 0x3377d1cf, v44
	v_fmac_f32_e32 v45, 0x3f317217, v44
	v_mov_b32_e32 v44, v45
	v_fma_f32 v45, v47, v51, v67
	v_max_f32_e32 v45, 0xda24260, v45
	v_log_f32_e32 v45, v45
	s_nop 0
	v_mul_f32_e32 v46, 0x3f317217, v45
	v_fma_f32 v46, v45, s13, -v46
	v_fmac_f32_e32 v46, 0x3377d1cf, v45
	v_fmac_f32_e32 v46, 0x3f317217, v45
	v_mov_b32_e32 v45, v46
	v_readlane_b32 s0, v253, 0
	v_readlane_b32 s1, v253, 1
	s_nop 0
	v_lshl_add_u64 v[46:47], v[98:99], 1, s[0:1]
	global_store_dwordx4 v[46:47], v[38:41], off
	s_mov_b64 s[0:1], 0
	s_nop 0
	v_lshl_add_u64 v[38:39], v[98:99], 2, s[2:3]
	global_store_dwordx4 v[38:39], v[26:29], off
	global_store_dwordx4 v[38:39], v[42:45], off offset:16

; __device__ __forceinline__ float silu_f(float x) { return x * __builtin_amdgcn_rcpf(1.f + __expf(-x)); }
; __device__ __forceinline__ v4u pack8(const float (&y)[8]) { return (v4u){pk2(y[0], y[1]), pk2(y[2], y[3]), pk2(y[4], y[5]), pk2(y[6], y[7])}; }
;     __device__ __forceinline__ void operator()(const f32x4 (&acc)[2][2][4][2], const pg8::Unit& u, int wr, int wc, int fr, int fq) const {
;     ...
;                         const int row = lrow0 + ai * 128 + m * 16; const size_t off = (size_t)row * 1024 + c;
;                         const f32x4 v0 = acc[ai][bj][m][0] * rs[ai][m], v1 = acc[ai][bj][m][1] * rs[ai][m];
;                         const float v[8] = {v0[0], v0[1], v0[2], v0[3], v1[0], v1[1], v1[2], v1[3]};
;                         float y[8];
;                         if (region == 0) {
; #pragma unroll
;                             for (int j = 0; j < 8; ++j) y[j] = silu_f(v[j]);
;                             *(v4u*)(o0 + off) = pack8(y);
;                         } else if (region == 1) {
;                             float lf[8];
; #pragma unroll
;                             for (int j = 0; j < 8; ++j) {
;                                 const float om = 1.f - lb[j];
;                                 const float fc = fminf(fmaxf(v[j], -80.f), 80.f);
;                                 const float e = __expf(-fc), sg = __builtin_amdgcn_rcpf(1.f + e);
;                                 y[j] = om * e * sg;
;                                 lf[j] = __logf(fmaxf(lb[j] + om * sg, 1e-30f));
;                             }
;                             *(v4u*)(o1 + off) = pack8(y);
;                             *(f32x4*)(of + off) = (f32x4){lf[0], lf[1], lf[2], lf[3]}; *(f32x4*)(of + off + 4) = (f32x4){lf[4], lf[5], lf[6], lf[7]};
.LBB0_1063:
	v_mov_b32_e32 v93, v92
	v_mov_b32_e32 v30, v92
	v_mov_b32_e32 v31, v92
	v_or_b32_e32 v90, v90, v94
	v_pk_mul_f32 v[26:27], v[24:25], v[30:31]
	v_pk_mul_f32 v[28:29], v[22:23], v[92:93]
	v_pk_mul_f32 v[22:23], v[20:21], v[30:31]
	v_pk_mul_f32 v[24:25], v[18:19], v[92:93]
	s_and_b64 vcc, exec, s[44:45]
	s_mov_b64 s[0:1], -1
	s_cbranch_vccnz .LBB0_1072
	s_and_b64 vcc, exec, s[42:43]
	s_cbranch_vccnz .LBB0_1066
	v_max_f32_e32 v18, v28, v28
	s_mov_b32 s28, 0xc2a00000
	v_med3_f32 v18, v18, s28, v195
	v_mul_f32_e32 v18, 0xbfb8aa3b, v18
	v_exp_f32_e32 v18, v18
	v_pk_add_f32 v[32:33], v[72:73], 1.0 op_sel_hi:[1,0] neg_lo:[1,0] neg_hi:[1,0]
	s_mov_b32 s13, 0x3f317217
	s_mov_b32 s15, 0x7f800000
	v_add_f32_e32 v19, 1.0, v18
	v_rcp_f32_e32 v20, v19
	v_max_f32_e32 v19, v29, v29
	v_med3_f32 v19, v19, s28, v195
	v_mul_f32_e32 v19, 0xbfb8aa3b, v19
	v_exp_f32_e32 v19, v19
	v_pk_add_f32 v[36:37], v[70:71], 1.0 op_sel_hi:[1,0] neg_lo:[1,0] neg_hi:[1,0]
	v_pk_add_f32 v[38:39], v[68:69], 1.0 op_sel_hi:[1,0] neg_lo:[1,0] neg_hi:[1,0]
	v_pk_add_f32 v[42:43], v[66:67], 1.0 op_sel_hi:[1,0] neg_lo:[1,0] neg_hi:[1,0]
	v_add_f32_e32 v21, 1.0, v19
	v_rcp_f32_e32 v21, v21
	v_pk_mul_f32 v[18:19], v[18:19], v[32:33]
	s_nop 0
	v_pk_mul_f32 v[30:31], v[20:21], v[18:19]
	v_fma_f32 v18, v20, v32, v72
	v_max_f32_e32 v18, 0xda24260, v18
	v_cvt_pk_bf16_f32 v30, v30, v31
	s_nop 0
	v_log_f32_e32 v18, v18
	s_nop 0
	v_mul_f32_e32 v19, 0x3f317217, v18
	v_fma_f32 v19, v18, s13, -v19
	v_fmac_f32_e32 v19, 0x3377d1cf, v18
	v_fmac_f32_e32 v19, 0x3f317217, v18
	v_mov_b32_e32 v18, v19
	v_fma_f32 v19, v21, v33, v73
	v_max_f32_e32 v19, 0xda24260, v19
	v_log_f32_e32 v19, v19
	s_nop 0
	v_mul_f32_e32 v20, 0x3f317217, v19
	v_fma_f32 v20, v19, s13, -v20
	v_fmac_f32_e32 v20, 0x3377d1cf, v19
	v_fmac_f32_e32 v20, 0x3f317217, v19
	v_mov_b32_e32 v19, v20
	v_max_f32_e32 v20, v26, v26
	v_med3_f32 v20, v20, s28, v195
	v_mul_f32_e32 v20, 0xbfb8aa3b, v20
	v_exp_f32_e32 v20, v20
	s_nop 0
	v_add_f32_e32 v21, 1.0, v20
	v_rcp_f32_e32 v34, v21
	v_max_f32_e32 v21, v27, v27
	v_med3_f32 v21, v21, s28, v195
	v_mul_f32_e32 v21, 0xbfb8aa3b, v21
	v_exp_f32_e32 v21, v21
	s_nop 0
	v_add_f32_e32 v32, 1.0, v21
	v_rcp_f32_e32 v35, v32
	v_pk_mul_f32 v[20:21], v[20:21], v[36:37]
	s_nop 0
	v_pk_mul_f32 v[32:33], v[34:35], v[20:21]
	v_fma_f32 v20, v34, v36, v70
	v_max_f32_e32 v20, 0xda24260, v20
	v_cvt_pk_bf16_f32 v31, v32, v33
	s_nop 0
	v_log_f32_e32 v20, v20
	s_nop 0
	v_mul_f32_e32 v21, 0x3f317217, v20
	v_fma_f32 v21, v20, s13, -v21
	v_fmac_f32_e32 v21, 0x3377d1cf, v20
	v_fmac_f32_e32 v21, 0x3f317217, v20
	v_mov_b32_e32 v20, v21
	v_fma_f32 v21, v35, v37, v71
	v_max_f32_e32 v21, 0xda24260, v21
	v_log_f32_e32 v21, v21
	s_nop 0
	v_mul_f32_e32 v34, 0x3f317217, v21
	v_fma_f32 v34, v21, s13, -v34
	v_fmac_f32_e32 v34, 0x3377d1cf, v21
	v_fmac_f32_e32 v34, 0x3f317217, v21
	v_mov_b32_e32 v21, v34
	v_max_f32_e32 v34, v24, v24
	v_med3_f32 v34, v34, s28, v195
	v_mul_f32_e32 v34, 0xbfb8aa3b, v34
	v_exp_f32_e32 v34, v34
	s_nop 0
	v_add_f32_e32 v35, 1.0, v34
	v_rcp_f32_e32 v36, v35
	v_max_f32_e32 v35, v25, v25
	v_med3_f32 v35, v35, s28, v195
	v_mul_f32_e32 v35, 0xbfb8aa3b, v35
	v_exp_f32_e32 v35, v35
	s_nop 0
	v_add_f32_e32 v37, 1.0, v35
	v_rcp_f32_e32 v37, v37
	v_pk_mul_f32 v[34:35], v[34:35], v[38:39]
	s_nop 0
	v_pk_mul_f32 v[40:41], v[36:37], v[34:35]
	v_fma_f32 v34, v36, v38, v68
	v_max_f32_e32 v34, 0xda24260, v34
	v_cvt_pk_bf16_f32 v32, v40, v41
	s_nop 0
	v_log_f32_e32 v34, v34
	s_nop 0
	v_mul_f32_e32 v35, 0x3f317217, v34
	v_fma_f32 v35, v34, s13, -v35
	v_fmac_f32_e32 v35, 0x3377d1cf, v34
	v_fmac_f32_e32 v35, 0x3f317217, v34
	v_mov_b32_e32 v34, v35
	v_fma_f32 v35, v37, v39, v69
	v_max_f32_e32 v35, 0xda24260, v35
	v_log_f32_e32 v35, v35
	s_nop 0
	v_mul_f32_e32 v36, 0x3f317217, v35
	v_fma_f32 v36, v35, s13, -v36
	v_fmac_f32_e32 v36, 0x3377d1cf, v35
	v_fmac_f32_e32 v36, 0x3f317217, v35
	v_mov_b32_e32 v35, v36
	v_max_f32_e32 v36, v22, v22
	v_med3_f32 v36, v36, s28, v195
	v_mul_f32_e32 v36, 0xbfb8aa3b, v36
	v_exp_f32_e32 v36, v36
	s_nop 0
	v_add_f32_e32 v37, 1.0, v36
	v_rcp_f32_e32 v38, v37
	v_max_f32_e32 v37, v23, v23
	v_med3_f32 v37, v37, s28, v195
	v_mul_f32_e32 v37, 0xbfb8aa3b, v37
	v_exp_f32_e32 v37, v37
	s_nop 0
	v_add_f32_e32 v39, 1.0, v37
	v_rcp_f32_e32 v39, v39
	v_pk_mul_f32 v[36:37], v[36:37], v[42:43]
	s_nop 0
	v_pk_mul_f32 v[44:45], v[38:39], v[36:37]
	v_fma_f32 v36, v38, v42, v66
	v_max_f32_e32 v36, 0xda24260, v36
	v_cvt_pk_bf16_f32 v33, v44, v45
	s_nop 0
	v_log_f32_e32 v36, v36
	s_nop 0
	v_mul_f32_e32 v37, 0x3f317217, v36
	v_fma_f32 v37, v36, s13, -v37
	v_fmac_f32_e32 v37, 0x3377d1cf, v36
	v_fmac_f32_e32 v37, 0x3f317217, v36
	v_mov_b32_e32 v36, v37
	v_fma_f32 v37, v39, v43, v67
	v_max_f32_e32 v37, 0xda24260, v37
	v_log_f32_e32 v37, v37
	s_nop 0
	v_mul_f32_e32 v38, 0x3f317217, v37
	v_fma_f32 v38, v37, s13, -v38
	v_fmac_f32_e32 v38, 0x3377d1cf, v37
	v_fmac_f32_e32 v38, 0x3f317217, v37
	v_mov_b32_e32 v37, v38
	v_readlane_b32 s0, v253, 0
	v_readlane_b32 s1, v253, 1
	s_nop 0
	v_lshl_add_u64 v[38:39], v[90:91], 1, s[0:1]
	global_store_dwordx4 v[38:39], v[30:33], off
	s_mov_b64 s[0:1], 0
	s_nop 0
	v_lshl_add_u64 v[30:31], v[90:91], 2, s[2:3]
	global_store_dwordx4 v[30:31], v[18:21], off
	global_store_dwordx4 v[30:31], v[34:37], off offset:16

; __device__ __forceinline__ float silu_f(float x) { return x * __builtin_amdgcn_rcpf(1.f + __expf(-x)); }
; __device__ __forceinline__ v4u pack8(const float (&y)[8]) { return (v4u){pk2(y[0], y[1]), pk2(y[2], y[3]), pk2(y[4], y[5]), pk2(y[6], y[7])}; }
;     __device__ __forceinline__ void operator()(const f32x4 (&acc)[2][2][4][2], const pg8::Unit& u, int wr, int wc, int fr, int fq) const {
;     ...
;                         const int row = lrow0 + ai * 128 + m * 16; const size_t off = (size_t)row * 1024 + c;
;                         const f32x4 v0 = acc[ai][bj][m][0] * rs[ai][m], v1 = acc[ai][bj][m][1] * rs[ai][m];
;                         const float v[8] = {v0[0], v0[1], v0[2], v0[3], v1[0], v1[1], v1[2], v1[3]};
;                         float y[8];
;                         if (region == 0) {
; #pragma unroll
;                             for (int j = 0; j < 8; ++j) y[j] = silu_f(v[j]);
;                             *(v4u*)(o0 + off) = pack8(y);
;                         } else if (region == 1) {
;                             float lf[8];
; #pragma unroll
;                             for (int j = 0; j < 8; ++j) {
;                                 const float om = 1.f - lb[j];
;                                 const float fc = fminf(fmaxf(v[j], -80.f), 80.f);
;                                 const float e = __expf(-fc), sg = __builtin_amdgcn_rcpf(1.f + e);
;                                 y[j] = om * e * sg;
;                                 lf[j] = __logf(fmaxf(lb[j] + om * sg, 1e-30f));
;                             }
;                             *(v4u*)(o1 + off) = pack8(y);
;                             *(f32x4*)(of + off) = (f32x4){lf[0], lf[1], lf[2], lf[3]}; *(f32x4*)(of + off + 4) = (f32x4){lf[4], lf[5], lf[6], lf[7]};
.LBB0_1074:
	v_mov_b32_e32 v85, v84
	v_mov_b32_e32 v22, v84
	v_mov_b32_e32 v23, v84
	v_or_b32_e32 v82, v82, v94
	v_pk_mul_f32 v[18:19], v[16:17], v[22:23]
	v_pk_mul_f32 v[20:21], v[14:15], v[84:85]
	v_pk_mul_f32 v[14:15], v[12:13], v[22:23]
	v_pk_mul_f32 v[16:17], v[10:11], v[84:85]
	s_and_b64 vcc, exec, s[44:45]
	s_mov_b64 s[0:1], -1
	s_cbranch_vccnz .LBB0_1083
	s_and_b64 vcc, exec, s[42:43]
	s_cbranch_vccnz .LBB0_1077
	v_max_f32_e32 v10, v20, v20
	s_mov_b32 s28, 0xc2a00000
	v_med3_f32 v10, v10, s28, v195
	v_mul_f32_e32 v10, 0xbfb8aa3b, v10
	v_exp_f32_e32 v10, v10
	v_pk_add_f32 v[24:25], v[72:73], 1.0 op_sel_hi:[1,0] neg_lo:[1,0] neg_hi:[1,0]
	s_mov_b32 s13, 0x3f317217
	s_mov_b32 s15, 0x7f800000
	v_add_f32_e32 v11, 1.0, v10
	v_rcp_f32_e32 v12, v11
	v_max_f32_e32 v11, v21, v21
	v_med3_f32 v11, v11, s28, v195
	v_mul_f32_e32 v11, 0xbfb8aa3b, v11
	v_exp_f32_e32 v11, v11
	v_pk_add_f32 v[28:29], v[70:71], 1.0 op_sel_hi:[1,0] neg_lo:[1,0] neg_hi:[1,0]
	v_pk_add_f32 v[30:31], v[68:69], 1.0 op_sel_hi:[1,0] neg_lo:[1,0] neg_hi:[1,0]
	v_pk_add_f32 v[34:35], v[66:67], 1.0 op_sel_hi:[1,0] neg_lo:[1,0] neg_hi:[1,0]
	v_add_f32_e32 v13, 1.0, v11
	v_rcp_f32_e32 v13, v13
	v_pk_mul_f32 v[10:11], v[10:11], v[24:25]
	s_nop 0
	v_pk_mul_f32 v[22:23], v[12:13], v[10:11]
	v_fma_f32 v10, v12, v24, v72
	v_max_f32_e32 v10, 0xda24260, v10
	v_cvt_pk_bf16_f32 v22, v22, v23
	s_nop 0
	v_log_f32_e32 v10, v10
	s_nop 0
	v_mul_f32_e32 v11, 0x3f317217, v10
	v_fma_f32 v11, v10, s13, -v11
	v_fmac_f32_e32 v11, 0x3377d1cf, v10
	v_fmac_f32_e32 v11, 0x3f317217, v10
	v_mov_b32_e32 v10, v11
	v_fma_f32 v11, v13, v25, v73
	v_max_f32_e32 v11, 0xda24260, v11
	v_log_f32_e32 v11, v11
	s_nop 0
	v_mul_f32_e32 v12, 0x3f317217, v11
	v_fma_f32 v12, v11, s13, -v12
	v_fmac_f32_e32 v12, 0x3377d1cf, v11
	v_fmac_f32_e32 v12, 0x3f317217, v11
	v_mov_b32_e32 v11, v12
	v_max_f32_e32 v12, v18, v18
	v_med3_f32 v12, v12, s28, v195
	v_mul_f32_e32 v12, 0xbfb8aa3b, v12
	v_exp_f32_e32 v12, v12
	s_nop 0
	v_add_f32_e32 v13, 1.0, v12
	v_rcp_f32_e32 v26, v13
	v_max_f32_e32 v13, v19, v19
	v_med3_f32 v13, v13, s28, v195
	v_mul_f32_e32 v13, 0xbfb8aa3b, v13
	v_exp_f32_e32 v13, v13
	s_nop 0
	v_add_f32_e32 v24, 1.0, v13
	v_rcp_f32_e32 v27, v24
	v_pk_mul_f32 v[12:13], v[12:13], v[28:29]
	s_nop 0
	v_pk_mul_f32 v[24:25], v[26:27], v[12:13]
	v_fma_f32 v12, v26, v28, v70
	v_max_f32_e32 v12, 0xda24260, v12
	v_cvt_pk_bf16_f32 v23, v24, v25
	s_nop 0
	v_log_f32_e32 v12, v12
	s_nop 0
	v_mul_f32_e32 v13, 0x3f317217, v12
	v_fma_f32 v13, v12, s13, -v13
	v_fmac_f32_e32 v13, 0x3377d1cf, v12
	v_fmac_f32_e32 v13, 0x3f317217, v12
	v_mov_b32_e32 v12, v13
	v_fma_f32 v13, v27, v29, v71
	v_max_f32_e32 v13, 0xda24260, v13
	v_log_f32_e32 v13, v13
	s_nop 0
	v_mul_f32_e32 v26, 0x3f317217, v13
	v_fma_f32 v26, v13, s13, -v26
	v_fmac_f32_e32 v26, 0x3377d1cf, v13
	v_fmac_f32_e32 v26, 0x3f317217, v13
	v_mov_b32_e32 v13, v26
	v_max_f32_e32 v26, v16, v16
	v_med3_f32 v26, v26, s28, v195
	v_mul_f32_e32 v26, 0xbfb8aa3b, v26
	v_exp_f32_e32 v26, v26
	s_nop 0
	v_add_f32_e32 v27, 1.0, v26
	v_rcp_f32_e32 v28, v27
	v_max_f32_e32 v27, v17, v17
	v_med3_f32 v27, v27, s28, v195
	v_mul_f32_e32 v27, 0xbfb8aa3b, v27
	v_exp_f32_e32 v27, v27
	s_nop 0
	v_add_f32_e32 v29, 1.0, v27
	v_rcp_f32_e32 v29, v29
	v_pk_mul_f32 v[26:27], v[26:27], v[30:31]
	s_nop 0
	v_pk_mul_f32 v[32:33], v[28:29], v[26:27]
	v_fma_f32 v26, v28, v30, v68
	v_max_f32_e32 v26, 0xda24260, v26
	v_cvt_pk_bf16_f32 v24, v32, v33
	s_nop 0
	v_log_f32_e32 v26, v26
	s_nop 0
	v_mul_f32_e32 v27, 0x3f317217, v26
	v_fma_f32 v27, v26, s13, -v27
	v_fmac_f32_e32 v27, 0x3377d1cf, v26
	v_fmac_f32_e32 v27, 0x3f317217, v26
	v_mov_b32_e32 v26, v27
	v_fma_f32 v27, v29, v31, v69
	v_max_f32_e32 v27, 0xda24260, v27
	v_log_f32_e32 v27, v27
	s_nop 0
	v_mul_f32_e32 v28, 0x3f317217, v27
	v_fma_f32 v28, v27, s13, -v28
	v_fmac_f32_e32 v28, 0x3377d1cf, v27
	v_fmac_f32_e32 v28, 0x3f317217, v27
	v_mov_b32_e32 v27, v28
	v_max_f32_e32 v28, v14, v14
	v_med3_f32 v28, v28, s28, v195
	v_mul_f32_e32 v28, 0xbfb8aa3b, v28
	v_exp_f32_e32 v28, v28
	s_nop 0
	v_add_f32_e32 v29, 1.0, v28
	v_rcp_f32_e32 v30, v29
	v_max_f32_e32 v29, v15, v15
	v_med3_f32 v29, v29, s28, v195
	v_mul_f32_e32 v29, 0xbfb8aa3b, v29
	v_exp_f32_e32 v29, v29
	s_nop 0
	v_add_f32_e32 v31, 1.0, v29
	v_rcp_f32_e32 v31, v31
	v_pk_mul_f32 v[28:29], v[28:29], v[34:35]
	s_nop 0
	v_pk_mul_f32 v[36:37], v[30:31], v[28:29]
	v_fma_f32 v28, v30, v34, v66
	v_max_f32_e32 v28, 0xda24260, v28
	v_cvt_pk_bf16_f32 v25, v36, v37
	s_nop 0
	v_log_f32_e32 v28, v28
	s_nop 0
	v_mul_f32_e32 v29, 0x3f317217, v28
	v_fma_f32 v29, v28, s13, -v29
	v_fmac_f32_e32 v29, 0x3377d1cf, v28
	v_fmac_f32_e32 v29, 0x3f317217, v28
	v_mov_b32_e32 v28, v29
	v_fma_f32 v29, v31, v35, v67
	v_max_f32_e32 v29, 0xda24260, v29
	v_log_f32_e32 v29, v29
	s_nop 0
	v_mul_f32_e32 v30, 0x3f317217, v29
	v_fma_f32 v30, v29, s13, -v30
	v_fmac_f32_e32 v30, 0x3377d1cf, v29
	v_fmac_f32_e32 v30, 0x3f317217, v29
	v_mov_b32_e32 v29, v30
	v_readlane_b32 s0, v253, 0
	v_readlane_b32 s1, v253, 1
	s_nop 0
	v_lshl_add_u64 v[30:31], v[82:83], 1, s[0:1]
	global_store_dwordx4 v[30:31], v[22:25], off
	s_mov_b64 s[0:1], 0
	s_nop 0
	v_lshl_add_u64 v[22:23], v[82:83], 2, s[2:3]
	global_store_dwordx4 v[22:23], v[10:13], off
	global_store_dwordx4 v[22:23], v[26:29], off offset:16

; __device__ __forceinline__ float silu_f(float x) { return x * __builtin_amdgcn_rcpf(1.f + __expf(-x)); }
; __device__ __forceinline__ v4u pack8(const float (&y)[8]) { return (v4u){pk2(y[0], y[1]), pk2(y[2], y[3]), pk2(y[4], y[5]), pk2(y[6], y[7])}; }
;     __device__ __forceinline__ void operator()(const f32x4 (&acc)[2][2][4][2], const pg8::Unit& u, int wr, int wc, int fr, int fq) const {
;     ...
;                         const int row = lrow0 + ai * 128 + m * 16; const size_t off = (size_t)row * 1024 + c;
;                         const f32x4 v0 = acc[ai][bj][m][0] * rs[ai][m], v1 = acc[ai][bj][m][1] * rs[ai][m];
;                         const float v[8] = {v0[0], v0[1], v0[2], v0[3], v1[0], v1[1], v1[2], v1[3]};
;                         float y[8];
;                         if (region == 0) {
; #pragma unroll
;                             for (int j = 0; j < 8; ++j) y[j] = silu_f(v[j]);
;                             *(v4u*)(o0 + off) = pack8(y);
;                         } else if (region == 1) {
;                             float lf[8];
; #pragma unroll
;                             for (int j = 0; j < 8; ++j) {
;                                 const float om = 1.f - lb[j];
;                                 const float fc = fminf(fmaxf(v[j], -80.f), 80.f);
;                                 const float e = __expf(-fc), sg = __builtin_amdgcn_rcpf(1.f + e);
;                                 y[j] = om * e * sg;
;                                 lf[j] = __logf(fmaxf(lb[j] + om * sg, 1e-30f));
;                             }
;                             *(v4u*)(o1 + off) = pack8(y);
;                             *(f32x4*)(of + off) = (f32x4){lf[0], lf[1], lf[2], lf[3]}; *(f32x4*)(of + off + 4) = (f32x4){lf[4], lf[5], lf[6], lf[7]};
.LBB0_1088:
	s_and_b64 vcc, exec, s[42:43]
	s_cbranch_vccnz .LBB0_1090
	v_max_f32_e32 v2, v12, v12
	s_mov_b32 s28, 0xc2a00000
	v_med3_f32 v2, v2, s28, v195
	v_mul_f32_e32 v2, 0xbfb8aa3b, v2
	v_exp_f32_e32 v2, v2
	v_pk_add_f32 v[16:17], v[72:73], 1.0 op_sel_hi:[1,0] neg_lo:[1,0] neg_hi:[1,0]
	s_mov_b32 s13, 0x3f317217
	s_mov_b32 s15, 0x7f800000
	v_add_f32_e32 v3, 1.0, v2
	v_rcp_f32_e32 v4, v3
	v_max_f32_e32 v3, v13, v13
	v_med3_f32 v3, v3, s28, v195
	v_mul_f32_e32 v3, 0xbfb8aa3b, v3
	v_exp_f32_e32 v3, v3
	v_fmac_f32_e32 v72, v4, v16
	v_pk_add_f32 v[20:21], v[70:71], 1.0 op_sel_hi:[1,0] neg_lo:[1,0] neg_hi:[1,0]
	v_pk_add_f32 v[22:23], v[68:69], 1.0 op_sel_hi:[1,0] neg_lo:[1,0] neg_hi:[1,0]
	v_add_f32_e32 v5, 1.0, v3
	v_rcp_f32_e32 v5, v5
	v_pk_mul_f32 v[2:3], v[2:3], v[16:17]
	v_pk_add_f32 v[26:27], v[66:67], 1.0 op_sel_hi:[1,0] neg_lo:[1,0] neg_hi:[1,0]
	v_pk_mul_f32 v[14:15], v[4:5], v[2:3]
	v_max_f32_e32 v2, 0xda24260, v72
	v_fmac_f32_e32 v73, v5, v17
	v_cvt_pk_bf16_f32 v14, v14, v15
	v_log_f32_e32 v2, v2
	s_nop 0
	v_mul_f32_e32 v3, 0x3f317217, v2
	v_fma_f32 v3, v2, s13, -v3
	v_fmac_f32_e32 v3, 0x3377d1cf, v2
	v_fmac_f32_e32 v3, 0x3f317217, v2
	v_mov_b32_e32 v2, v3
	v_max_f32_e32 v3, 0xda24260, v73
	v_log_f32_e32 v3, v3
	s_nop 0
	v_mul_f32_e32 v4, 0x3f317217, v3
	v_fma_f32 v4, v3, s13, -v4
	v_fmac_f32_e32 v4, 0x3377d1cf, v3
	v_fmac_f32_e32 v4, 0x3f317217, v3
	v_mov_b32_e32 v3, v4
	v_max_f32_e32 v4, v10, v10
	v_med3_f32 v4, v4, s28, v195
	v_mul_f32_e32 v4, 0xbfb8aa3b, v4
	v_exp_f32_e32 v4, v4
	s_nop 0
	v_add_f32_e32 v5, 1.0, v4
	v_rcp_f32_e32 v18, v5
	v_max_f32_e32 v5, v11, v11
	v_med3_f32 v5, v5, s28, v195
	v_mul_f32_e32 v5, 0xbfb8aa3b, v5
	v_exp_f32_e32 v5, v5
	v_fmac_f32_e32 v70, v18, v20
	v_add_f32_e32 v16, 1.0, v5
	v_rcp_f32_e32 v19, v16
	v_pk_mul_f32 v[4:5], v[4:5], v[20:21]
	v_fmac_f32_e32 v71, v19, v21
	v_pk_mul_f32 v[16:17], v[18:19], v[4:5]
	v_max_f32_e32 v4, 0xda24260, v70
	v_cvt_pk_bf16_f32 v15, v16, v17
	s_nop 0
	v_log_f32_e32 v4, v4
	s_nop 0
	v_mul_f32_e32 v5, 0x3f317217, v4
	v_fma_f32 v5, v4, s13, -v5
	v_fmac_f32_e32 v5, 0x3377d1cf, v4
	v_fmac_f32_e32 v5, 0x3f317217, v4
	v_mov_b32_e32 v4, v5
	v_max_f32_e32 v5, 0xda24260, v71
	v_log_f32_e32 v5, v5
	s_nop 0
	v_mul_f32_e32 v18, 0x3f317217, v5
	v_fma_f32 v18, v5, s13, -v18
	v_fmac_f32_e32 v18, 0x3377d1cf, v5
	v_fmac_f32_e32 v18, 0x3f317217, v5
	v_mov_b32_e32 v5, v18
	v_max_f32_e32 v18, v8, v8
	v_med3_f32 v18, v18, s28, v195
	v_mul_f32_e32 v18, 0xbfb8aa3b, v18
	v_exp_f32_e32 v18, v18
	s_nop 0
	v_add_f32_e32 v19, 1.0, v18
	v_rcp_f32_e32 v20, v19
	v_max_f32_e32 v19, v9, v9
	v_med3_f32 v19, v19, s28, v195
	v_mul_f32_e32 v19, 0xbfb8aa3b, v19
	v_exp_f32_e32 v19, v19
	v_fmac_f32_e32 v68, v20, v22
	v_add_f32_e32 v21, 1.0, v19
	v_rcp_f32_e32 v21, v21
	v_pk_mul_f32 v[18:19], v[18:19], v[22:23]
	v_fmac_f32_e32 v69, v21, v23
	v_pk_mul_f32 v[24:25], v[20:21], v[18:19]
	v_max_f32_e32 v18, 0xda24260, v68
	v_cvt_pk_bf16_f32 v16, v24, v25
	s_nop 0
	v_log_f32_e32 v18, v18
	s_nop 0
	v_mul_f32_e32 v19, 0x3f317217, v18
	v_fma_f32 v19, v18, s13, -v19
	v_fmac_f32_e32 v19, 0x3377d1cf, v18
	v_fmac_f32_e32 v19, 0x3f317217, v18
	v_mov_b32_e32 v18, v19
	v_max_f32_e32 v19, 0xda24260, v69
	v_log_f32_e32 v19, v19
	s_nop 0
	v_mul_f32_e32 v20, 0x3f317217, v19
	v_fma_f32 v20, v19, s13, -v20
	v_fmac_f32_e32 v20, 0x3377d1cf, v19
	v_fmac_f32_e32 v20, 0x3f317217, v19
	v_mov_b32_e32 v19, v20
	v_max_f32_e32 v20, v6, v6
	v_med3_f32 v20, v20, s28, v195
	v_mul_f32_e32 v20, 0xbfb8aa3b, v20
	v_exp_f32_e32 v20, v20
	s_nop 0
	v_add_f32_e32 v21, 1.0, v20
	v_rcp_f32_e32 v22, v21
	v_max_f32_e32 v21, v7, v7
	v_med3_f32 v21, v21, s28, v195
	v_mul_f32_e32 v21, 0xbfb8aa3b, v21
	v_exp_f32_e32 v21, v21
	v_fmac_f32_e32 v66, v22, v26
	v_add_f32_e32 v23, 1.0, v21
	v_rcp_f32_e32 v23, v23
	v_pk_mul_f32 v[20:21], v[20:21], v[26:27]
	v_fmac_f32_e32 v67, v23, v27
	v_pk_mul_f32 v[28:29], v[22:23], v[20:21]
	v_max_f32_e32 v20, 0xda24260, v66
	v_cvt_pk_bf16_f32 v17, v28, v29
	s_nop 0
	v_log_f32_e32 v20, v20
	s_nop 0
	v_mul_f32_e32 v21, 0x3f317217, v20
	v_fma_f32 v21, v20, s13, -v21
	v_fmac_f32_e32 v21, 0x3377d1cf, v20
	v_fmac_f32_e32 v21, 0x3f317217, v20
	v_mov_b32_e32 v20, v21
	v_max_f32_e32 v21, 0xda24260, v67
	v_log_f32_e32 v21, v21
	s_nop 0
	v_mul_f32_e32 v22, 0x3f317217, v21
	v_fma_f32 v22, v21, s13, -v22
	v_fmac_f32_e32 v22, 0x3377d1cf, v21
	v_fmac_f32_e32 v22, 0x3f317217, v21
	v_mov_b32_e32 v21, v22
	v_readlane_b32 s0, v253, 0
	v_readlane_b32 s1, v253, 1
	s_nop 0
	v_lshl_add_u64 v[22:23], v[74:75], 1, s[0:1]
	global_store_dwordx4 v[22:23], v[14:17], off
	s_mov_b64 s[0:1], 0
	s_nop 0
	v_lshl_add_u64 v[14:15], v[74:75], 2, s[2:3]
	global_store_dwordx4 v[14:15], v[2:5], off
	global_store_dwordx4 v[14:15], v[18:21], off offset:16
